# scheduling lever: per-segment s_setprio flips of the four K-loops deleted, one static s_setprio 1 for waves 4-7
# baseline (speedup 1.0000x reference)
; __device__ __forceinline__ unsigned xb_ld(unsigned* p)              { return __hip_atomic_load(p, __ATOMIC_RELAXED, __HIP_MEMORY_SCOPE_AGENT); }
; __device__ __forceinline__ unsigned xb_add(unsigned* p, unsigned v) { return __hip_atomic_fetch_add(p, v, __ATOMIC_RELAXED, __HIP_MEMORY_SCOPE_AGENT); }
; __device__ __forceinline__ void xcd_barrier_complete(unsigned* bar, unsigned x, unsigned& nloc, unsigned& nx) {
;     const unsigned G = gridDim.x * gridDim.y * gridDim.z;
;     unsigned sum, cnt, mine, sp = 0u;
;     for (;;) {
;         sum = 0u; cnt = 0u; mine = 0u;
; #pragma unroll
;         for (unsigned j = 0; j < 16; ++j) { const unsigned c = xb_ld(&bar[XB_XCNT(j)]); sum += c; cnt += (c > 0u) ? 1u : 0u; mine = (j == x) ? c : mine; }
;         if (sum == G) break;
;         __builtin_amdgcn_s_sleep(1);
;         if ((++sp & 255u) == 0u) { if (xb_ld(&bar[XB_TMO])) break; if (sp > XB_SPIN_CAP) { atomicAdd(&bar[XB_TMO], 1u); break; } }
;     }
;     nloc = mine > 0u ? mine : 1u; nx = cnt > 0u ? cnt : 1u;
; }
; __device__ __forceinline__ void xcd_barrier(const XcdBarrier& b) {
;     asm volatile("s_waitcnt vmcnt(0)" ::: "memory");
;     __syncthreads();
;     if (threadIdx.x == 0) {
;         unsigned* bar = b.bar;
;         __builtin_amdgcn_s_waitcnt(0);
;         unsigned nloc = b.st[0], nx = b.st[1];
;         if (nloc == 0u) { xcd_barrier_complete(bar, b.x, nloc, nx); b.st[0] = nloc; b.st[1] = nx; }
;         const unsigned old = xb_add(&bar[XB_XSUB(b.x)], 1u);
;         const unsigned gen = old / nloc;
;         if (old + 1u == (gen + 1u) * nloc) {
;             __builtin_amdgcn_fence(__ATOMIC_RELEASE, "agent");
;             asm volatile("s_waitcnt vmcnt(0)" ::: "memory");
;             const unsigned og = xb_add(&bar[XB_TOP], 1u);
;             const unsigned tg = og / nx;
;             if (og + 1u == (tg + 1u) * nx) xb_add(&bar[XB_TOPGEN], 1u);
;             else XB_SPIN(xb_ld(&bar[XB_TOPGEN]) == tg, bar);
;             __builtin_amdgcn_fence(__ATOMIC_ACQUIRE, "agent");
;             xb_add(&bar[XB_XGEN(b.x)], 1u);
;             asm volatile("s_waitcnt vmcnt(0)" ::: "memory");
;         } else {
;             XB_SPIN(xb_ld(&bar[XB_XGEN(b.x)]) == gen, bar);
;             __builtin_amdgcn_fence(__ATOMIC_ACQUIRE, "agent");
;             asm volatile("s_waitcnt vmcnt(0)" ::: "memory");
;         }
.Lpl_done:
	v_writelane_b32 v255, s4, 26
	v_readfirstlane_b32 s4, v174
	s_nop 3
	s_cmp_ge_u32 s4, 0x100
	s_cbranch_scc0 .Lprio_done
	s_setprio 1
.Lprio_done:
	s_add_u32 s4, s44, 0x4600
	s_addc_u32 s5, s45, 0
	v_writelane_b32 v251, s4, 42
	v_mov_b32_e32 v145, 0
	s_nop 0
	v_writelane_b32 v251, s5, 43
	s_add_u32 s4, s44, 0x4700
	s_addc_u32 s5, s45, 0
	v_writelane_b32 v251, s4, 44
	v_mov_b32_e32 v176, 1
	v_mov_b32_e32 v177, 0x3ab69700
	v_writelane_b32 v251, s5, 45
	s_add_u32 s4, s44, 0x4800
	s_addc_u32 s5, s45, 0
	v_writelane_b32 v251, s4, 46
	v_mov_b32_e32 v178, 0x260
	v_mov_b32_e32 v179, 0x358637bd
	v_writelane_b32 v251, s5, 47
	s_add_u32 s4, s44, 0x4900
	s_addc_u32 s5, s45, 0
	v_writelane_b32 v251, s4, 48
	v_mbcnt_hi_u32_b32 v175, -1, v22
	v_mov_b32_e32 v192, 0x42800000
	v_writelane_b32 v251, s5, 49
	s_add_u32 s4, s44, 0x4a00
	s_addc_u32 s5, s45, 0
	v_writelane_b32 v251, s4, 50
	v_mov_b32_e32 v193, 0x42000000
	v_mov_b32_e32 v194, 0x2400
	v_writelane_b32 v251, s5, 51
	s_add_u32 s4, s44, 0x4b00
	s_addc_u32 s5, s45, 0
	v_writelane_b32 v251, s4, 52
	v_mov_b32_e32 v195, 0x7f000000
	v_not_b32_e32 v196, 63
	v_writelane_b32 v251, s5, 53
	s_add_u32 s4, s44, 0x4c00
	s_addc_u32 s5, s45, 0
	v_writelane_b32 v251, s4, 54
	v_mov_b64_e32 v[146:147], 0x100
	v_mov_b64_e32 v[148:149], 0xff
	v_writelane_b32 v251, s5, 55
	s_add_u32 s4, s44, 0x4d00
	s_addc_u32 s5, s45, 0
	v_writelane_b32 v251, s4, 56
	s_mov_b32 s33, 0x800000
	s_movk_i32 s84, 0x1600
	v_writelane_b32 v251, s5, 57
	s_add_u32 s4, s44, 0x4e00
	s_addc_u32 s5, s45, 0
	v_writelane_b32 v251, s4, 58
	s_movk_i32 s85, 0x2c00
	s_mov_b32 s87, 0xc2fc0000
	v_writelane_b32 v251, s5, 59
	s_add_u32 s4, s44, 0x4f00
	s_addc_u32 s5, s45, 0
	v_writelane_b32 v251, s4, 60
	s_mov_b32 s86, 0x42b17217
	s_mov_b64 s[94:95], 0x80
	v_writelane_b32 v251, s5, 61
	s_add_u32 s4, s44, 0x5000
	s_addc_u32 s5, s45, 0
	v_writelane_b32 v251, s4, 62
	s_mov_b32 s82, s83
	s_nop 0
	v_writelane_b32 v251, s5, 63
	s_add_u32 s4, s44, 0x5100
	s_addc_u32 s5, s45, 0
	v_writelane_b32 v252, s4, 0
	s_nop 1
	v_writelane_b32 v252, s5, 1
	s_add_u32 s4, s44, 0x5200
	s_addc_u32 s5, s45, 0
	v_writelane_b32 v252, s4, 2
	s_nop 1
	v_writelane_b32 v252, s5, 3
	s_add_u32 s4, s44, 0x5300
	s_addc_u32 s5, s45, 0
	v_writelane_b32 v252, s4, 4
	s_cmp_eq_u32 s3, 15
	s_nop 0
	v_writelane_b32 v252, s5, 5
	s_cselect_b64 s[4:5], -1, 0
	v_writelane_b32 v252, s4, 6
	s_cmp_eq_u32 s3, 14
	s_nop 0
	v_writelane_b32 v252, s5, 7
	s_cselect_b64 s[4:5], -1, 0
	v_writelane_b32 v252, s4, 8
	s_cmp_eq_u32 s3, 13
	s_nop 0
	v_writelane_b32 v252, s5, 9
	s_cselect_b64 s[4:5], -1, 0
	v_writelane_b32 v252, s4, 10
	s_cmp_eq_u32 s3, 12
	s_nop 0
	v_writelane_b32 v252, s5, 11
	s_cselect_b64 s[4:5], -1, 0
	v_writelane_b32 v252, s4, 12
	s_cmp_eq_u32 s3, 11
	s_nop 0
	v_writelane_b32 v252, s5, 13
	s_cselect_b64 s[4:5], -1, 0
	v_writelane_b32 v252, s4, 14
	s_cmp_eq_u32 s3, 10
	s_nop 0
	v_writelane_b32 v252, s5, 15
	s_cselect_b64 s[4:5], -1, 0
	v_writelane_b32 v252, s4, 16
	s_cmp_eq_u32 s3, 9
	s_nop 0
	v_writelane_b32 v252, s5, 17
	s_cselect_b64 s[4:5], -1, 0
	v_writelane_b32 v252, s4, 18
	s_cmp_eq_u32 s3, 8
	s_nop 0
	v_writelane_b32 v252, s5, 19
	s_cselect_b64 s[4:5], -1, 0
	v_writelane_b32 v252, s4, 20
	s_cmp_eq_u32 s3, 7
	s_nop 0
	v_writelane_b32 v252, s5, 21
	s_cselect_b64 s[4:5], -1, 0
	v_writelane_b32 v252, s4, 22
	s_cmp_eq_u32 s3, 6
	s_nop 0
	v_writelane_b32 v252, s5, 23
	s_cselect_b64 s[4:5], -1, 0
	v_writelane_b32 v252, s4, 24
	s_cmp_eq_u32 s3, 5
	s_nop 0
	v_writelane_b32 v252, s5, 25
	s_cselect_b64 s[4:5], -1, 0
	v_writelane_b32 v252, s4, 26
	s_cmp_eq_u32 s3, 4
	s_nop 0
	v_writelane_b32 v252, s5, 27
	s_cselect_b64 s[4:5], -1, 0
	v_writelane_b32 v252, s4, 28
	s_cmp_eq_u32 s3, 3
	s_nop 0
	v_writelane_b32 v252, s5, 29
	s_cselect_b64 s[4:5], -1, 0
	v_writelane_b32 v252, s4, 30
	s_cmp_eq_u32 s3, 2
	s_nop 0
	v_writelane_b32 v252, s5, 31
	s_cselect_b64 s[4:5], -1, 0
	v_writelane_b32 v252, s4, 32
	s_cmp_eq_u32 s3, 1
	s_nop 0
	v_writelane_b32 v252, s5, 33
	s_cselect_b64 s[4:5], -1, 0
	v_writelane_b32 v252, s4, 34
	s_cmp_eq_u32 s3, 0
	s_nop 0
	v_writelane_b32 v252, s5, 35
	s_cselect_b64 s[4:5], -1, 0
	v_writelane_b32 v252, s4, 36
	s_lshl_b32 s3, s3, 8
	s_nop 0
	v_writelane_b32 v252, s5, 37
	v_readlane_b32 s4, v251, 11
	v_readlane_b32 s5, v251, 12
	s_add_u32 s3, s4, s3
	s_addc_u32 s4, s5, 0
	s_add_u32 s12, s3, 0x1400
	s_addc_u32 s13, s4, 0
	v_writelane_b32 v252, s12, 38
	s_nop 1
	v_writelane_b32 v252, s13, 39
	s_add_u32 s12, s3, 0x2400
	s_addc_u32 s13, s4, 0
	v_writelane_b32 v252, s12, 40
	s_add_u32 s4, s44, 0x7400
	s_addc_u32 s5, s45, 0
	v_writelane_b32 v252, s13, 41
	v_writelane_b32 v252, s4, 42
	s_movk_i32 s12, 0xb1
	s_nop 0
	v_writelane_b32 v252, s5, 43
	s_add_u32 s4, s44, 0x7500
	s_addc_u32 s5, s45, 0
	v_writelane_b32 v252, s4, 44
	s_cmpk_lt_i32 s89, 0x300
	s_nop 0
	v_writelane_b32 v252, s5, 45
	s_cselect_b64 s[4:5], -1, 0
	v_writelane_b32 v252, s4, 46
	s_nop 1
	v_writelane_b32 v252, s5, 47
	s_add_u32 s4, s44, 0x14e00000
	s_addc_u32 s5, s45, 0
	v_writelane_b32 v252, s4, 48
	s_nop 1
	v_writelane_b32 v252, s5, 49
	s_add_u32 s4, s44, 0x600000
	s_addc_u32 s5, s45, 0
	v_writelane_b32 v252, s4, 50
	s_add_u32 s3, s44, 0x900000
	s_nop 0
	v_writelane_b32 v252, s5, 51
	v_writelane_b32 v252, s3, 52
	s_addc_u32 s3, s45, 0
	s_add_u32 s4, s44, 0x840000
	v_writelane_b32 v252, s3, 53
	s_addc_u32 s5, s45, 0
	v_writelane_b32 v252, s4, 54
	s_nop 1
	v_writelane_b32 v252, s5, 55
	s_add_u32 s4, s44, 0x800000
	s_addc_u32 s5, s45, 0
	v_writelane_b32 v252, s4, 56
;     __host__ __device__ bool next(int i, Unit& u) const {
;         const long L = (long)i * G + c; if (L >= nwg) return false;
;         int wgid = (int)L; { const int q = nwg / NXCD, r = nwg % NXCD, xcd = wgid % NXCD, off = wgid / NXCD; wgid = (xcd < r ? xcd * (q + 1) : r * (q + 1) + (xcd - r) * q) + off; }
;         const int nig = WGM * nN, gid = wgid / nig, fm = gid * WGM, gsz = (nM - fm) < WGM ? (nM - fm) : WGM;
;         u.pm = fm + ((wgid % nig) % gsz); u.pn = (wgid % nig) / gsz; return true;
; template <class Epi, class Sched, bool ALIGN_EPI = false, bool SP2 = false>
; __device__ __forceinline__ void gemm_phase(PG8_LAS unsigned char* lds, const Gemm g, const Sched& S, const Epi& E) {
;     ...
;     const char* cA = (const char*)g.A + (size_t)cur.pm * tstep; const char* cB = (const char*)g.Bt + (size_t)cur.pn * tstep;
	s_nop 1
	v_writelane_b32 v252, s5, 57
	v_readlane_b32 s4, v251, 23
	s_add_i32 s3, s4, 0xfffff600
	v_readlane_b32 s5, v251, 24
	s_add_u32 s4, s44, 0x16e00000
	s_addc_u32 s5, s45, 0
	v_writelane_b32 v251, s4, 11
	s_cmpk_lt_i32 s89, 0x100
	v_writelane_b32 v252, s3, 58
	v_writelane_b32 v251, s5, 12
	s_cselect_b64 s[4:5], -1, 0
	s_lshl_b32 s3, s7, 5
	v_writelane_b32 v252, s4, 59
	s_cmpk_lt_i32 s89, 0x580
	s_nop 0
	v_writelane_b32 v252, s5, 60
	s_cselect_b64 s[4:5], -1, 0
	v_writelane_b32 v252, s4, 61
	s_cmpk_gt_u32 s89, 0x7f
	s_nop 0
	v_writelane_b32 v252, s5, 62
	s_cselect_b64 s[4:5], -1, 0
	s_cmp_lt_i32 s7, 0
	s_cselect_b32 s3, s24, s3
	s_cselect_b32 s24, s88, 0x58
	s_mul_i32 s24, s7, s24
	s_cselect_b32 s25, s12, 0xb0
	s_add_i32 s24, s24, s6
	s_mul_hi_i32 s26, s24, 0x2e8ba2e9
	s_lshr_b32 s27, s26, 31
	s_ashr_i32 s26, s26, 3
	s_add_i32 s26, s26, s27
	s_mul_i32 s27, s26, 44
	s_sub_i32 s24, s24, s27
	s_bfe_i32 s27, s24, 0x80000
	s_bfe_u32 s27, s27, 0x2000d
	s_add_i32 s27, s24, s27
	s_and_b32 s28, s27, 0xfc
	s_add_i32 s3, s3, s6
	s_sub_i32 s24, s24, s28
	s_ashr_i32 s28, s3, 31
	s_mul_i32 s7, s7, s25
	s_lshr_b32 s28, s28, 28
	s_add_i32 s7, s7, s6
	s_add_i32 s28, s3, s28
	s_mul_hi_i32 s6, s7, 0x2e8ba2e9
	s_and_b32 s29, s28, 0xfff0
	s_lshr_b32 s25, s6, 31
	s_ashr_i32 s6, s6, 4
	s_sub_i32 s3, s3, s29
	s_add_i32 s6, s6, s25
	s_bfe_i32 s29, s3, 0x80000
	s_mul_i32 s25, s6, 0x58
	v_readlane_b32 s12, v251, 16
	s_bfe_u32 s29, s29, 0x2000d
	s_sub_i32 s7, s7, s25
	v_readlane_b32 s13, v251, 17
	s_add_i32 s29, s3, s29
	s_bfe_i32 s25, s7, 0x80000
	s_and_b64 s[0:1], s[0:1], s[12:13]
	s_and_b32 s30, s29, 0xfc
	s_bfe_u32 s25, s25, 0x2000d
	v_writelane_b32 v252, s0, 63
	s_sub_i32 s3, s3, s30
	s_add_i32 s25, s7, s25
	s_lshl_b32 s26, s26, 2
	s_sext_i32_i8 s24, s24
	v_writelane_b32 v253, s1, 0
	s_ashr_i32 s0, s28, 4
	s_bfe_i32 s1, s29, 0x80000
	s_and_b32 s30, s25, 0xfc
	s_add_i32 s16, s26, s24
	s_lshl_b32 s0, s0, 2
	s_sext_i32_i16 s24, s1
	s_sext_i32_i8 s1, s3
	s_sub_i32 s7, s7, s30
	s_add_i32 s18, s0, s1
	s_bfe_i32 s1, s25, 0x80000
	s_lshl_b32 s0, s6, 2
	s_sext_i32_i16 s1, s1
	s_sext_i32_i8 s3, s7
	s_add_i32 s22, s0, s3
	s_ashr_i32 s0, s1, 2
	v_writelane_b32 v253, s0, 1
	s_lshr_b32 s0, s1, 2
	s_bfe_i64 s[0:1], s[0:1], 0x100000
	s_bfe_i32 s27, s27, 0x80000
	s_lshl_b64 s[0:1], s[0:1], 19
	s_sext_i32_i16 s27, s27
	v_writelane_b32 v253, s0, 2
	s_ashr_i32 s23, s22, 31
	s_mov_b32 s20, s22
	v_writelane_b32 v253, s1, 3
	s_ashr_i32 s0, s27, 2
	v_writelane_b32 v253, s0, 4
	s_lshr_b32 s0, s27, 2
	s_ashr_i32 s3, s24, 2
	s_lshr_b32 s6, s24, 2
	v_writelane_b32 v253, s20, 5
	s_lshl_b64 s[24:25], s[22:23], 19
	s_nop 0
	v_writelane_b32 v253, s21, 6
	s_add_u32 s20, s10, s24
	s_addc_u32 s21, s11, s25
	s_add_u32 s22, s20, 0x40000
	v_writelane_b32 v253, s20, 7
	s_addc_u32 s23, s21, 0
	s_and_b64 s[4:5], s[4:5], s[12:13]
	v_writelane_b32 v253, s21, 8
	v_writelane_b32 v253, s22, 9
	s_bfe_i64 s[0:1], s[0:1], 0x100000
	s_lshl_b64 s[0:1], s[0:1], 19
	v_writelane_b32 v253, s23, 10
	v_writelane_b32 v253, s4, 11
	s_ashr_i32 s17, s16, 31
	s_nop 0
	v_writelane_b32 v253, s5, 12
	v_writelane_b32 v253, s0, 13
	s_nop 1
	v_writelane_b32 v253, s1, 14
	s_mov_b32 s0, s16
	v_writelane_b32 v253, s0, 15
	s_nop 1
	v_writelane_b32 v253, s1, 16
	s_lshl_b64 s[0:1], s[16:17], 19
	s_add_u32 s0, s10, s0
	s_addc_u32 s1, s11, s1
	s_add_u32 s4, s0, 0x40000
	v_writelane_b32 v253, s0, 17
	s_addc_u32 s5, s1, 0
	s_ashr_i32 s19, s18, 31
	v_writelane_b32 v253, s1, 18
	v_writelane_b32 v253, s4, 19
	s_bfe_i64 s[0:1], s[6:7], 0x100000
	s_lshl_b64 s[0:1], s[0:1], 19
	v_writelane_b32 v253, s5, 20
	v_writelane_b32 v253, s0, 21
	s_nop 1
	v_writelane_b32 v253, s1, 22
	s_lshl_b32 s0, s18, 8
	v_writelane_b32 v253, s0, 23
	v_writelane_b32 v253, s3, 24
	s_lshl_b32 s0, s3, 8
	v_writelane_b32 v253, s0, 25
	s_lshl_b64 s[0:1], s[18:19], 19
	s_add_u32 s4, s78, s0
	s_addc_u32 s5, s79, s1
	s_mul_i32 s0, s47, s46
	v_readlane_b32 s1, v250, 8
	s_mul_i32 s0, s0, s1
	v_writelane_b32 v250, s0, 8
	s_add_u32 s0, s4, 0x40000
	v_writelane_b32 v253, s4, 26
	s_addc_u32 s1, s5, 0
	s_nop 0
	v_writelane_b32 v253, s5, 27
	v_writelane_b32 v253, s0, 28
	s_mov_b32 s4, s18
	s_nop 0
	v_writelane_b32 v253, s1, 29
	v_writelane_b32 v253, s4, 30
	s_mul_i32 s1, s18, 0x160000
	s_mul_hi_i32 s0, s18, 0x160000
	v_writelane_b32 v253, s5, 31
	s_add_u32 s4, s8, s1
	s_addc_u32 s5, s9, s0
	s_add_u32 s0, s4, 0xb0000
	v_writelane_b32 v253, s4, 32
	s_addc_u32 s1, s5, 0
	s_nop 0
	v_writelane_b32 v253, s5, 33
	v_writelane_b32 v253, s0, 34
	s_nop 1
	v_writelane_b32 v253, s1, 35
	s_lshl_b32 s0, s89, 4
	s_add_i32 s0, s0, 0x7fffc500
	v_writelane_b32 v253, s0, 36
	s_add_i32 s0, s2, 0xffffdd00
	v_writelane_b32 v253, s0, 37
	s_lshl_b32 s0, s89, 8
	v_writelane_b32 v253, s0, 38
	s_add_u32 s0, s44, 0x847c00
	s_addc_u32 s1, s45, 0
	v_writelane_b32 v253, s0, 39
	s_mov_b32 s2, 0x43000000
	s_nop 0
	v_writelane_b32 v253, s1, 40
	s_add_u32 s0, s44, 0xd600300
	s_addc_u32 s1, s45, 0
	v_writelane_b32 v253, s0, 41
	s_nop 1
	v_writelane_b32 v253, s1, 42
	s_add_u32 s0, s44, 0x12e00240
	v_writelane_b32 v253, s0, 43
	s_addc_u32 s0, s45, 0
	v_writelane_b32 v253, s0, 44
	s_add_i32 s0, 0, 0x20000
	v_writelane_b32 v253, s0, 45
	s_add_i32 s0, 0, 0x25fe0
	v_writelane_b32 v253, s0, 46
	s_add_i32 s0, 0, 0x25fe4
	v_writelane_b32 v253, s0, 47
	s_add_i32 s0, 0, 0xcc00
	v_writelane_b32 v253, s0, 48
	v_writelane_b32 v253, s14, 49
	s_add_i32 s97, 0, 0x15400
	s_add_i32 s96, 0, 0x1dc00
	s_add_i32 s3, 0, 0x19000
	v_writelane_b32 v253, s15, 50
	s_branch .LBB0_231

; #define PG8_STAGE(bufoff, gbase, voff) do { _Pragma("unroll") for (int _i = 0; _i < 2; ++_i) \
;         __builtin_amdgcn_global_load_lds((const unsigned*)((const char*)(gbase) + (voff)[_i]), (PG8_LAS unsigned*)(lds + (bufoff) + ldsw + _i * 8192), 16, 0, 0); } while (0)
; #define PG8_LDA(dst, b, h) do { _Pragma("unroll") for (int m = 0; m < 4; ++m) _Pragma("unroll") for (int k = 0; k < 2; ++k) dst[m][k] = *(const PG8_LAS bf16x8*)(lds + PG8_SA(b, h) + aoff + m * 2048 + k * 1024); } while (0)
; #define PG8_LDB(dst, b, h) do { _Pragma("unroll") for (int n = 0; n < 2; ++n) _Pragma("unroll") for (int k = 0; k < 2; ++k) dst[n][k] = *(const PG8_LAS bf16x8*)(lds + PG8_SB(b, h) + boff + n * 2048 + k * 1024); } while (0)
; #define PG8_MMA(ai, bj, At, Bt) do { __builtin_amdgcn_s_setprio(1); _Pragma("unroll") for (int m = 0; m < 4; ++m) _Pragma("unroll") for (int n = 0; n < 2; ++n) _Pragma("unroll") for (int k = 0; k < 2; ++k) \
;         acc[ai][bj][m][n] = __builtin_amdgcn_mfma_f32_16x16x32_bf16(Bt[n][k], At[m][k], acc[ai][bj][m][n], 0, 0, 0); __builtin_amdgcn_s_setprio(0); } while (0)
; #define PG8_WAIT_V(n) asm volatile("s_waitcnt vmcnt(" #n ")" ::: "memory")
; #define PG8_BAR __builtin_amdgcn_s_barrier()
; template <class Epi, class Sched, bool ALIGN_EPI = false, bool SP2 = false>
; __device__ __forceinline__ void gemm_phase(PG8_LAS unsigned char* lds, const Gemm g, const Sched& S, const Epi& E) {
;     ...
;             const bool last = (t == nt - 2);
;             const char* a1 = cA + (size_t)(t + 1) * kstep;
;             const char* a2 = last ? nA : cA + (size_t)(t + 2) * kstep; const char* b2 = last ? nB : cB + (size_t)(t + 2) * kstep;
;             const char* a3 = a2 + kstep; const char* b3 = b2 + kstep;
;             if (last && has_next) S.a_ready(nxt);
;             if (last) E.pre(cur, wid, lane);
;             if constexpr (SP2) {
;             PG8_LDB(B0, 0, 0); PG8_LDB(B1, 0, 1); PG8_SCHED; PG8_LDA(At, 0, 0); PG8_STAGE(PG8_SA(1, 1), a1 + hstep, voffA);
;             PG8_WAIT_V(8); PG8_WAIT_L(0); PG8_BAR; PG8_MMA(0, 0, At, B0); PG8_MMA(0, 1, At, B1); PG8_BAR; PG8_SCHED;
;             PG8_LDA(At, 0, 1); PG8_STAGE(PG8_SB(0, 0), b2, voffB); PG8_STAGE(PG8_SB(0, 1), b2 + hstep, voffB); PG8_STAGE(PG8_SA(0, 0), a2, voffA);
;             PG8_WAIT_V(8); PG8_WAIT_L(0); PG8_BAR; PG8_MMA(1, 0, At, B0); PG8_MMA(1, 1, At, B1); PG8_BAR; PG8_SCHED;
.LBB0_244:
	s_add_u32 s6, s4, 0xfffc0080
	s_addc_u32 s7, s5, -1
	s_and_b64 s[0:1], s[0:1], exec
	s_cselect_b32 s7, s38, s7
	s_cselect_b32 s6, s39, s6
	s_cselect_b32 s1, s49, s57
	s_cselect_b32 s0, s55, s56
	s_add_i32 s59, 0, 0x10000
	v_add_u32_e32 v144, s59, v197
	s_add_i32 s62, 0, 0x14000
	ds_read_b128 v[132:135], v144
	ds_read_b128 v[136:139], v144 offset:1024
	ds_read_b128 v[140:143], v144 offset:2048
	ds_read_b128 v[202:205], v144 offset:3072
	v_add_u32_e32 v144, s62, v197
	ds_read_b128 v[206:209], v144
	ds_read_b128 v[210:213], v144 offset:1024
	ds_read_b128 v[214:217], v144 offset:2048
	ds_read_b128 v[218:221], v144 offset:3072
	v_lshl_add_u64 v[172:173], s[4:5], 0, v[166:167]
	s_add_i32 m0, s25, 0xc000
	ds_read_b128 v[222:225], v199
	ds_read_b128 v[226:229], v199 offset:1024
	ds_read_b128 v[230:233], v199 offset:2048
	ds_read_b128 v[234:237], v199 offset:3072
	ds_read_b128 v[238:241], v199 offset:4096
	ds_read_b128 v[242:245], v199 offset:5120
	ds_read_b128 v[246:249], v199 offset:6144
	ds_read_b128 v[180:183], v199 offset:7168
	global_load_lds_dwordx4 v[172:173], off
	v_lshl_add_u64 v[172:173], s[4:5], 0, v[168:169]
	s_add_i32 m0, s25, 0xe000
	s_nop 0
	global_load_lds_dwordx4 v[172:173], off
	s_waitcnt vmcnt(8)
	s_waitcnt lgkmcnt(0)
	.p2alignl 3, 3212836864
	s_barrier
	v_mfma_f32_16x16x32_bf16 v[124:127], v[132:135], v[222:225], v[124:127]
	v_mfma_f32_16x16x32_bf16 v[120:123], v[140:143], v[222:225], v[120:123]
	v_mfma_f32_16x16x32_bf16 v[108:111], v[132:135], v[230:233], v[108:111]
	v_mfma_f32_16x16x32_bf16 v[104:107], v[140:143], v[230:233], v[104:107]
	v_mfma_f32_16x16x32_bf16 v[92:95], v[132:135], v[238:241], v[92:95]
	v_mfma_f32_16x16x32_bf16 v[88:91], v[140:143], v[238:241], v[88:91]
	v_mfma_f32_16x16x32_bf16 v[76:79], v[132:135], v[246:249], v[76:79]
	v_mfma_f32_16x16x32_bf16 v[72:75], v[140:143], v[246:249], v[72:75]
	v_mfma_f32_16x16x32_bf16 v[124:127], v[136:139], v[226:229], v[124:127]
	v_mfma_f32_16x16x32_bf16 v[120:123], v[202:205], v[226:229], v[120:123]
	v_mfma_f32_16x16x32_bf16 v[108:111], v[136:139], v[234:237], v[108:111]
	v_mfma_f32_16x16x32_bf16 v[104:107], v[202:205], v[234:237], v[104:107]
	v_mfma_f32_16x16x32_bf16 v[92:95], v[136:139], v[242:245], v[92:95]
	v_mfma_f32_16x16x32_bf16 v[88:91], v[202:205], v[242:245], v[88:91]
	v_mfma_f32_16x16x32_bf16 v[76:79], v[136:139], v[180:183], v[76:79]
	v_mfma_f32_16x16x32_bf16 v[72:75], v[202:205], v[180:183], v[72:75]
	v_mfma_f32_16x16x32_bf16 v[116:119], v[206:209], v[222:225], v[116:119]
	v_mfma_f32_16x16x32_bf16 v[112:115], v[214:217], v[222:225], v[112:115]
	v_mfma_f32_16x16x32_bf16 v[100:103], v[206:209], v[230:233], v[100:103]
	v_mfma_f32_16x16x32_bf16 v[96:99], v[214:217], v[230:233], v[96:99]
	v_mfma_f32_16x16x32_bf16 v[84:87], v[206:209], v[238:241], v[84:87]
	v_mfma_f32_16x16x32_bf16 v[80:83], v[214:217], v[238:241], v[80:83]
	v_mfma_f32_16x16x32_bf16 v[68:71], v[206:209], v[246:249], v[68:71]
	v_mfma_f32_16x16x32_bf16 v[64:67], v[214:217], v[246:249], v[64:67]
	v_mfma_f32_16x16x32_bf16 v[116:119], v[210:213], v[226:229], v[116:119]
	v_mfma_f32_16x16x32_bf16 v[112:115], v[218:221], v[226:229], v[112:115]
	v_mfma_f32_16x16x32_bf16 v[100:103], v[210:213], v[234:237], v[100:103]
	v_mfma_f32_16x16x32_bf16 v[96:99], v[218:221], v[234:237], v[96:99]
	v_mfma_f32_16x16x32_bf16 v[84:87], v[210:213], v[242:245], v[84:87]
	v_mfma_f32_16x16x32_bf16 v[80:83], v[218:221], v[242:245], v[80:83]
	v_mfma_f32_16x16x32_bf16 v[68:71], v[210:213], v[180:183], v[68:71]
	v_mfma_f32_16x16x32_bf16 v[64:67], v[218:221], v[180:183], v[64:67]
	s_barrier
	s_add_i32 s59, s59, s24
	v_lshl_add_u64 v[172:173], s[0:1], 0, v[154:155]
	s_mov_b32 m0, s59
	ds_read_b128 v[180:183], v199 offset:16384
	ds_read_b128 v[222:225], v199 offset:17408
	ds_read_b128 v[226:229], v199 offset:18432
	ds_read_b128 v[230:233], v199 offset:19456
	ds_read_b128 v[234:237], v199 offset:20480
	ds_read_b128 v[238:241], v199 offset:21504
	ds_read_b128 v[242:245], v199 offset:22528
	ds_read_b128 v[246:249], v199 offset:23552
	global_load_lds_dwordx4 v[172:173], off
	s_add_i32 m0, s59, 0x2000
	s_add_u32 s60, s0, 0x40000
	v_lshl_add_u64 v[184:185], s[0:1], 0, v[150:151]
	s_addc_u32 s61, s1, 0
	s_add_i32 s59, s62, s24
	global_load_lds_dwordx4 v[184:185], off
	v_lshl_add_u64 v[186:187], s[60:61], 0, v[154:155]
	s_mov_b32 m0, s59
	v_lshl_add_u64 v[188:189], s[6:7], 0, v[152:153]
	global_load_lds_dwordx4 v[186:187], off
	v_lshl_add_u64 v[186:187], s[60:61], 0, v[150:151]
	s_add_i32 m0, s59, 0x2000
	s_nop 0
	global_load_lds_dwordx4 v[186:187], off
	v_lshl_add_u64 v[186:187], s[6:7], 0, v[156:157]
	s_mov_b32 m0, s25
	s_nop 0
	global_load_lds_dwordx4 v[186:187], off
	s_mov_b32 m0, s26
	s_nop 0
	global_load_lds_dwordx4 v[188:189], off
	s_waitcnt vmcnt(8)
	s_waitcnt lgkmcnt(0)
	.p2alignl 3, 3212836864
	s_barrier
; #define PG8_STAGE(bufoff, gbase, voff) do { _Pragma("unroll") for (int _i = 0; _i < 2; ++_i) \
;         __builtin_amdgcn_global_load_lds((const unsigned*)((const char*)(gbase) + (voff)[_i]), (PG8_LAS unsigned*)(lds + (bufoff) + ldsw + _i * 8192), 16, 0, 0); } while (0)
; #define PG8_LDA(dst, b, h) do { _Pragma("unroll") for (int m = 0; m < 4; ++m) _Pragma("unroll") for (int k = 0; k < 2; ++k) dst[m][k] = *(const PG8_LAS bf16x8*)(lds + PG8_SA(b, h) + aoff + m * 2048 + k * 1024); } while (0)
; #define PG8_LDB(dst, b, h) do { _Pragma("unroll") for (int n = 0; n < 2; ++n) _Pragma("unroll") for (int k = 0; k < 2; ++k) dst[n][k] = *(const PG8_LAS bf16x8*)(lds + PG8_SB(b, h) + boff + n * 2048 + k * 1024); } while (0)
; #define PG8_MMA(ai, bj, At, Bt) do { __builtin_amdgcn_s_setprio(1); _Pragma("unroll") for (int m = 0; m < 4; ++m) _Pragma("unroll") for (int n = 0; n < 2; ++n) _Pragma("unroll") for (int k = 0; k < 2; ++k) \
;         acc[ai][bj][m][n] = __builtin_amdgcn_mfma_f32_16x16x32_bf16(Bt[n][k], At[m][k], acc[ai][bj][m][n], 0, 0, 0); __builtin_amdgcn_s_setprio(0); } while (0)
; #define PG8_WAIT_V(n) asm volatile("s_waitcnt vmcnt(" #n ")" ::: "memory")
; #define PG8_WAIT_L(n) asm volatile("s_waitcnt lgkmcnt(" #n ")" ::: "memory")
; #define PG8_BAR __builtin_amdgcn_s_barrier()
; #define PG8_SCHED __builtin_amdgcn_sched_barrier(0)
; template <class Epi, class Sched, bool ALIGN_EPI = false, bool SP2 = false>
; __device__ __forceinline__ void gemm_phase(PG8_LAS unsigned char* lds, const Gemm g, const Sched& S, const Epi& E) {
;     ...
;             PG8_WAIT_V(8); PG8_WAIT_L(0); PG8_BAR; PG8_MMA(1, 0, At, B0); PG8_MMA(1, 1, At, B1); PG8_BAR; PG8_SCHED;
;             PG8_LDB(B0, 1, 0); PG8_LDB(B1, 1, 1); PG8_SCHED; PG8_LDA(At, 1, 0); PG8_STAGE(PG8_SA(0, 1), a2 + hstep, voffA);
;             PG8_WAIT_V(8); PG8_WAIT_L(0); PG8_BAR; PG8_MMA(0, 0, At, B0); PG8_MMA(0, 1, At, B1); PG8_BAR; PG8_SCHED;
	v_mfma_f32_16x16x32_bf16 v[60:63], v[132:135], v[180:183], v[60:63]
	v_mfma_f32_16x16x32_bf16 v[56:59], v[140:143], v[180:183], v[56:59]
	v_mfma_f32_16x16x32_bf16 v[44:47], v[132:135], v[226:229], v[44:47]
	v_mfma_f32_16x16x32_bf16 v[40:43], v[140:143], v[226:229], v[40:43]
	v_mfma_f32_16x16x32_bf16 v[28:31], v[132:135], v[234:237], v[28:31]
	v_mfma_f32_16x16x32_bf16 v[24:27], v[140:143], v[234:237], v[24:27]
	v_mfma_f32_16x16x32_bf16 v[12:15], v[132:135], v[242:245], v[12:15]
	v_mfma_f32_16x16x32_bf16 v[8:11], v[140:143], v[242:245], v[8:11]
	v_mfma_f32_16x16x32_bf16 v[60:63], v[136:139], v[222:225], v[60:63]
	v_mfma_f32_16x16x32_bf16 v[56:59], v[202:205], v[222:225], v[56:59]
	v_mfma_f32_16x16x32_bf16 v[44:47], v[136:139], v[230:233], v[44:47]
	v_mfma_f32_16x16x32_bf16 v[40:43], v[202:205], v[230:233], v[40:43]
	v_mfma_f32_16x16x32_bf16 v[28:31], v[136:139], v[238:241], v[28:31]
	v_mfma_f32_16x16x32_bf16 v[24:27], v[202:205], v[238:241], v[24:27]
	v_mfma_f32_16x16x32_bf16 v[12:15], v[136:139], v[246:249], v[12:15]
	v_mfma_f32_16x16x32_bf16 v[8:11], v[202:205], v[246:249], v[8:11]
	v_mfma_f32_16x16x32_bf16 v[52:55], v[206:209], v[180:183], v[52:55]
	v_mfma_f32_16x16x32_bf16 v[48:51], v[214:217], v[180:183], v[48:51]
	v_mfma_f32_16x16x32_bf16 v[36:39], v[206:209], v[226:229], v[36:39]
	v_mfma_f32_16x16x32_bf16 v[32:35], v[214:217], v[226:229], v[32:35]
	v_mfma_f32_16x16x32_bf16 v[20:23], v[206:209], v[234:237], v[20:23]
	v_mfma_f32_16x16x32_bf16 v[16:19], v[214:217], v[234:237], v[16:19]
	v_mfma_f32_16x16x32_bf16 v[4:7], v[206:209], v[242:245], v[4:7]
	v_mfma_f32_16x16x32_bf16 v[0:3], v[214:217], v[242:245], v[0:3]
	v_mfma_f32_16x16x32_bf16 v[52:55], v[210:213], v[222:225], v[52:55]
	v_mfma_f32_16x16x32_bf16 v[48:51], v[218:221], v[222:225], v[48:51]
	v_mfma_f32_16x16x32_bf16 v[36:39], v[210:213], v[230:233], v[36:39]
	v_mfma_f32_16x16x32_bf16 v[32:35], v[218:221], v[230:233], v[32:35]
	v_mfma_f32_16x16x32_bf16 v[20:23], v[210:213], v[238:241], v[20:23]
	v_mfma_f32_16x16x32_bf16 v[16:19], v[218:221], v[238:241], v[16:19]
	v_mfma_f32_16x16x32_bf16 v[4:7], v[210:213], v[246:249], v[4:7]
	v_mfma_f32_16x16x32_bf16 v[0:3], v[218:221], v[246:249], v[0:3]
	s_barrier
	s_add_i32 s59, 0, 0x18000
	v_add_u32_e32 v144, s59, v197
	s_add_i32 s60, 0, 0x1c000
	ds_read_b128 v[132:135], v144
	ds_read_b128 v[136:139], v144 offset:1024
	ds_read_b128 v[140:143], v144 offset:2048
	ds_read_b128 v[180:183], v144 offset:3072
	v_add_u32_e32 v144, s60, v197
	ds_read_b128 v[202:205], v144
	ds_read_b128 v[206:209], v144 offset:1024
	ds_read_b128 v[210:213], v144 offset:2048
	ds_read_b128 v[214:217], v144 offset:3072
	s_add_u32 s6, s6, 0x40000
	s_addc_u32 s7, s7, 0
	s_mov_b32 m0, s27
	v_lshl_add_u64 v[190:191], s[6:7], 0, v[156:157]
	ds_read_b128 v[218:221], v199 offset:32768
	ds_read_b128 v[222:225], v199 offset:33792
	ds_read_b128 v[226:229], v199 offset:34816
	ds_read_b128 v[230:233], v199 offset:35840
	ds_read_b128 v[234:237], v199 offset:36864
	ds_read_b128 v[238:241], v199 offset:37888
	ds_read_b128 v[242:245], v199 offset:38912
	ds_read_b128 v[246:249], v199 offset:39936
	global_load_lds_dwordx4 v[190:191], off
	v_lshl_add_u64 v[190:191], s[6:7], 0, v[152:153]
	s_mov_b32 m0, s28
	s_nop 0
	global_load_lds_dwordx4 v[190:191], off
	s_waitcnt vmcnt(8)
	s_waitcnt lgkmcnt(0)
	.p2alignl 3, 3212836864
	s_barrier
	v_mfma_f32_16x16x32_bf16 v[124:127], v[132:135], v[218:221], v[124:127]
	v_mfma_f32_16x16x32_bf16 v[120:123], v[140:143], v[218:221], v[120:123]
	v_mfma_f32_16x16x32_bf16 v[108:111], v[132:135], v[226:229], v[108:111]
	v_mfma_f32_16x16x32_bf16 v[104:107], v[140:143], v[226:229], v[104:107]
	v_mfma_f32_16x16x32_bf16 v[92:95], v[132:135], v[234:237], v[92:95]
	v_mfma_f32_16x16x32_bf16 v[88:91], v[140:143], v[234:237], v[88:91]
	v_mfma_f32_16x16x32_bf16 v[76:79], v[132:135], v[242:245], v[76:79]
	v_mfma_f32_16x16x32_bf16 v[72:75], v[140:143], v[242:245], v[72:75]
	v_mfma_f32_16x16x32_bf16 v[124:127], v[136:139], v[222:225], v[124:127]
	v_mfma_f32_16x16x32_bf16 v[120:123], v[180:183], v[222:225], v[120:123]
	v_mfma_f32_16x16x32_bf16 v[108:111], v[136:139], v[230:233], v[108:111]
	v_mfma_f32_16x16x32_bf16 v[104:107], v[180:183], v[230:233], v[104:107]
	v_mfma_f32_16x16x32_bf16 v[92:95], v[136:139], v[238:241], v[92:95]
	v_mfma_f32_16x16x32_bf16 v[88:91], v[180:183], v[238:241], v[88:91]
	v_mfma_f32_16x16x32_bf16 v[76:79], v[136:139], v[246:249], v[76:79]
	v_mfma_f32_16x16x32_bf16 v[72:75], v[180:183], v[246:249], v[72:75]
	v_mfma_f32_16x16x32_bf16 v[116:119], v[202:205], v[218:221], v[116:119]
	v_mfma_f32_16x16x32_bf16 v[112:115], v[210:213], v[218:221], v[112:115]
	v_mfma_f32_16x16x32_bf16 v[100:103], v[202:205], v[226:229], v[100:103]
	v_mfma_f32_16x16x32_bf16 v[96:99], v[210:213], v[226:229], v[96:99]
	v_mfma_f32_16x16x32_bf16 v[84:87], v[202:205], v[234:237], v[84:87]
	v_mfma_f32_16x16x32_bf16 v[80:83], v[210:213], v[234:237], v[80:83]
	v_mfma_f32_16x16x32_bf16 v[68:71], v[202:205], v[242:245], v[68:71]
	v_mfma_f32_16x16x32_bf16 v[64:67], v[210:213], v[242:245], v[64:67]
	v_mfma_f32_16x16x32_bf16 v[116:119], v[206:209], v[222:225], v[116:119]
	v_mfma_f32_16x16x32_bf16 v[112:115], v[214:217], v[222:225], v[112:115]
	v_mfma_f32_16x16x32_bf16 v[100:103], v[206:209], v[230:233], v[100:103]
	v_mfma_f32_16x16x32_bf16 v[96:99], v[214:217], v[230:233], v[96:99]
	v_mfma_f32_16x16x32_bf16 v[84:87], v[206:209], v[238:241], v[84:87]
	v_mfma_f32_16x16x32_bf16 v[80:83], v[214:217], v[238:241], v[80:83]
	v_mfma_f32_16x16x32_bf16 v[68:71], v[206:209], v[246:249], v[68:71]
	v_mfma_f32_16x16x32_bf16 v[64:67], v[214:217], v[246:249], v[64:67]
	s_barrier
; #define PG8_STAGE(bufoff, gbase, voff) do { _Pragma("unroll") for (int _i = 0; _i < 2; ++_i) \
;         __builtin_amdgcn_global_load_lds((const unsigned*)((const char*)(gbase) + (voff)[_i]), (PG8_LAS unsigned*)(lds + (bufoff) + ldsw + _i * 8192), 16, 0, 0); } while (0)
; #define PG8_LDA(dst, b, h) do { _Pragma("unroll") for (int m = 0; m < 4; ++m) _Pragma("unroll") for (int k = 0; k < 2; ++k) dst[m][k] = *(const PG8_LAS bf16x8*)(lds + PG8_SA(b, h) + aoff + m * 2048 + k * 1024); } while (0)
; #define PG8_MMA(ai, bj, At, Bt) do { __builtin_amdgcn_s_setprio(1); _Pragma("unroll") for (int m = 0; m < 4; ++m) _Pragma("unroll") for (int n = 0; n < 2; ++n) _Pragma("unroll") for (int k = 0; k < 2; ++k) \
;         acc[ai][bj][m][n] = __builtin_amdgcn_mfma_f32_16x16x32_bf16(Bt[n][k], At[m][k], acc[ai][bj][m][n], 0, 0, 0); __builtin_amdgcn_s_setprio(0); } while (0)
; #define PG8_WAIT_V(n) asm volatile("s_waitcnt vmcnt(" #n ")" ::: "memory")
; #define PG8_WAIT_L(n) asm volatile("s_waitcnt lgkmcnt(" #n ")" ::: "memory")
; #define PG8_BAR __builtin_amdgcn_s_barrier()
; #define PG8_SCHED __builtin_amdgcn_sched_barrier(0)
; template <class Epi, class Sched, bool ALIGN_EPI = false, bool SP2 = false>
; __device__ __forceinline__ void gemm_phase(PG8_LAS unsigned char* lds, const Gemm g, const Sched& S, const Epi& E) {
;     ...
;             PG8_LDA(At, 1, 1); PG8_STAGE(PG8_SB(1, 0), b3, voffB); PG8_STAGE(PG8_SB(1, 1), b3 + hstep, voffB); PG8_STAGE(PG8_SA(1, 0), a3, voffA);
;             PG8_WAIT_V(8); PG8_WAIT_L(0); PG8_BAR; PG8_MMA(1, 0, At, B0); PG8_MMA(1, 1, At, B1); PG8_BAR; PG8_SCHED;
	s_add_i32 s6, s59, s24
	v_lshl_add_u64 v[172:173], v[172:173], 0, s[94:95]
	s_mov_b32 m0, s6
	ds_read_b128 v[218:221], v199 offset:49152
	ds_read_b128 v[222:225], v199 offset:50176
	ds_read_b128 v[226:229], v199 offset:51200
	ds_read_b128 v[230:233], v199 offset:52224
	ds_read_b128 v[234:237], v199 offset:53248
	ds_read_b128 v[238:241], v199 offset:54272
	ds_read_b128 v[242:245], v199 offset:55296
	ds_read_b128 v[246:249], v199 offset:56320
	global_load_lds_dwordx4 v[172:173], off
	s_add_i32 m0, s6, 0x2000
	s_add_u32 s0, s0, 0x40080
	v_lshl_add_u64 v[172:173], v[184:185], 0, s[94:95]
	s_addc_u32 s1, s1, 0
	s_add_i32 s6, s60, s24
	global_load_lds_dwordx4 v[172:173], off
	v_lshl_add_u64 v[172:173], s[0:1], 0, v[154:155]
	s_mov_b32 m0, s6
	s_nop 0
	global_load_lds_dwordx4 v[172:173], off
	v_lshl_add_u64 v[172:173], s[0:1], 0, v[150:151]
	s_add_i32 m0, s6, 0x2000
	s_nop 0
	global_load_lds_dwordx4 v[172:173], off
	v_lshl_add_u64 v[172:173], v[186:187], 0, s[94:95]
	s_mov_b32 m0, s29
	s_nop 0
	global_load_lds_dwordx4 v[172:173], off
	v_lshl_add_u64 v[172:173], v[188:189], 0, s[94:95]
	s_mov_b32 m0, s30
	s_nop 0
	global_load_lds_dwordx4 v[172:173], off
	s_waitcnt vmcnt(8)
	s_waitcnt lgkmcnt(0)
	.p2alignl 3, 3212836864
	s_barrier
	v_mfma_f32_16x16x32_bf16 v[60:63], v[132:135], v[218:221], v[60:63]
	v_mfma_f32_16x16x32_bf16 v[56:59], v[140:143], v[218:221], v[56:59]
	v_mfma_f32_16x16x32_bf16 v[44:47], v[132:135], v[226:229], v[44:47]
	v_mfma_f32_16x16x32_bf16 v[40:43], v[140:143], v[226:229], v[40:43]
	v_mfma_f32_16x16x32_bf16 v[28:31], v[132:135], v[234:237], v[28:31]
	v_mfma_f32_16x16x32_bf16 v[24:27], v[140:143], v[234:237], v[24:27]
	v_mfma_f32_16x16x32_bf16 v[12:15], v[132:135], v[242:245], v[12:15]
	v_mfma_f32_16x16x32_bf16 v[8:11], v[140:143], v[242:245], v[8:11]
	v_mfma_f32_16x16x32_bf16 v[60:63], v[136:139], v[222:225], v[60:63]
	v_mfma_f32_16x16x32_bf16 v[56:59], v[180:183], v[222:225], v[56:59]
	v_mfma_f32_16x16x32_bf16 v[44:47], v[136:139], v[230:233], v[44:47]
	v_mfma_f32_16x16x32_bf16 v[40:43], v[180:183], v[230:233], v[40:43]
	v_mfma_f32_16x16x32_bf16 v[28:31], v[136:139], v[238:241], v[28:31]
	v_mfma_f32_16x16x32_bf16 v[24:27], v[180:183], v[238:241], v[24:27]
	v_mfma_f32_16x16x32_bf16 v[12:15], v[136:139], v[246:249], v[12:15]
	v_mfma_f32_16x16x32_bf16 v[8:11], v[180:183], v[246:249], v[8:11]
	v_mfma_f32_16x16x32_bf16 v[52:55], v[202:205], v[218:221], v[52:55]
	v_mfma_f32_16x16x32_bf16 v[48:51], v[210:213], v[218:221], v[48:51]
	v_mfma_f32_16x16x32_bf16 v[36:39], v[202:205], v[226:229], v[36:39]
	v_mfma_f32_16x16x32_bf16 v[32:35], v[210:213], v[226:229], v[32:35]
	v_mfma_f32_16x16x32_bf16 v[20:23], v[202:205], v[234:237], v[20:23]
	v_mfma_f32_16x16x32_bf16 v[16:19], v[210:213], v[234:237], v[16:19]
	v_mfma_f32_16x16x32_bf16 v[4:7], v[202:205], v[242:245], v[4:7]
	v_mfma_f32_16x16x32_bf16 v[0:3], v[210:213], v[242:245], v[0:3]
	v_mfma_f32_16x16x32_bf16 v[52:55], v[206:209], v[222:225], v[52:55]
	v_mfma_f32_16x16x32_bf16 v[48:51], v[214:217], v[222:225], v[48:51]
	v_mfma_f32_16x16x32_bf16 v[36:39], v[206:209], v[230:233], v[36:39]
	v_mfma_f32_16x16x32_bf16 v[32:35], v[214:217], v[230:233], v[32:35]
	v_mfma_f32_16x16x32_bf16 v[20:23], v[206:209], v[238:241], v[20:23]
	v_mfma_f32_16x16x32_bf16 v[16:19], v[214:217], v[238:241], v[16:19]
	v_mfma_f32_16x16x32_bf16 v[4:7], v[206:209], v[246:249], v[4:7]
	v_mfma_f32_16x16x32_bf16 v[0:3], v[214:217], v[246:249], v[0:3]
	s_barrier
	s_add_i32 s58, s58, 2
	s_add_u32 s4, s4, 0x100
	s_addc_u32 s5, s5, 0
	s_add_u32 s56, s56, 0x100
	s_addc_u32 s57, s57, 0
	s_cmp_gt_u32 s58, 13
	s_cbranch_scc1 .LBB0_247

; #define PG8_STAGE(bufoff, gbase, voff) do { _Pragma("unroll") for (int _i = 0; _i < 2; ++_i) \
;         __builtin_amdgcn_global_load_lds((const unsigned*)((const char*)(gbase) + (voff)[_i]), (PG8_LAS unsigned*)(lds + (bufoff) + ldsw + _i * 8192), 16, 0, 0); } while (0)
; #define PG8_LDA(dst, b, h) do { _Pragma("unroll") for (int m = 0; m < 4; ++m) _Pragma("unroll") for (int k = 0; k < 2; ++k) dst[m][k] = *(const PG8_LAS bf16x8*)(lds + PG8_SA(b, h) + aoff + m * 2048 + k * 1024); } while (0)
; #define PG8_LDB(dst, b, h) do { _Pragma("unroll") for (int n = 0; n < 2; ++n) _Pragma("unroll") for (int k = 0; k < 2; ++k) dst[n][k] = *(const PG8_LAS bf16x8*)(lds + PG8_SB(b, h) + boff + n * 2048 + k * 1024); } while (0)
; #define PG8_MMA(ai, bj, At, Bt) do { __builtin_amdgcn_s_setprio(1); _Pragma("unroll") for (int m = 0; m < 4; ++m) _Pragma("unroll") for (int n = 0; n < 2; ++n) _Pragma("unroll") for (int k = 0; k < 2; ++k) \
;         acc[ai][bj][m][n] = __builtin_amdgcn_mfma_f32_16x16x32_bf16(Bt[n][k], At[m][k], acc[ai][bj][m][n], 0, 0, 0); __builtin_amdgcn_s_setprio(0); } while (0)
; #define PG8_WAIT_V(n) asm volatile("s_waitcnt vmcnt(" #n ")" ::: "memory")
; #define PG8_BAR __builtin_amdgcn_s_barrier()
; template <class Epi, class Sched, bool ALIGN_EPI = false, bool SP2 = false>
; __device__ __forceinline__ void gemm_phase(PG8_LAS unsigned char* lds, const Gemm g, const Sched& S, const Epi& E) {
;     ...
;             const bool last = (t == nt - 2);
;             const char* a1 = cA + (size_t)(t + 1) * kstep;
;             const char* a2 = last ? nA : cA + (size_t)(t + 2) * kstep; const char* b2 = last ? nB : cB + (size_t)(t + 2) * kstep;
;             const char* a3 = a2 + kstep; const char* b3 = b2 + kstep;
;             if (last && has_next) S.a_ready(nxt);
;             if (last) E.pre(cur, wid, lane);
;             if constexpr (SP2) {
;             PG8_LDB(B0, 0, 0); PG8_LDB(B1, 0, 1); PG8_SCHED; PG8_LDA(At, 0, 0); PG8_STAGE(PG8_SA(1, 1), a1 + hstep, voffA);
;             PG8_WAIT_V(8); PG8_WAIT_L(0); PG8_BAR; PG8_MMA(0, 0, At, B0); PG8_MMA(0, 1, At, B1); PG8_BAR; PG8_SCHED;
;             PG8_LDA(At, 0, 1); PG8_STAGE(PG8_SB(0, 0), b2, voffB); PG8_STAGE(PG8_SB(0, 1), b2 + hstep, voffB); PG8_STAGE(PG8_SA(0, 0), a2, voffA);
;             PG8_WAIT_V(8); PG8_WAIT_L(0); PG8_BAR; PG8_MMA(1, 0, At, B0); PG8_MMA(1, 1, At, B1); PG8_BAR; PG8_SCHED;
.LBB0_1562:
	s_add_u32 s0, s28, 0xfffc0080
	s_addc_u32 s1, s29, -1
	s_add_i32 s58, 0, 0x10000
	s_cmp_eq_u32 s57, 12
	s_cselect_b32 s7, s47, s1
	s_cselect_b32 s6, s53, s0
	s_cselect_b32 s1, s45, s56
	s_cselect_b32 s0, s54, s55
	s_add_i32 s60, 0, 0x14000
	v_add_u32_e32 v160, s58, v143
	v_add_u32_e32 v172, s60, v143
	ds_read_b128 v[138:141], v160
	ds_read_b128 v[152:155], v160 offset:1024
	ds_read_b128 v[156:159], v160 offset:2048
	ds_read_b128 v[160:163], v160 offset:3072
	ds_read_b128 v[164:167], v172
	ds_read_b128 v[168:171], v172 offset:1024
	ds_read_b128 v[180:183], v172 offset:2048
	ds_read_b128 v[198:201], v172 offset:3072
	v_lshl_add_u64 v[172:173], s[28:29], 0, v[134:135]
	s_add_i32 m0, s26, 0xc000
	ds_read_b128 v[202:205], v151
	ds_read_b128 v[206:209], v151 offset:1024
	ds_read_b128 v[210:213], v151 offset:2048
	ds_read_b128 v[214:217], v151 offset:3072
	ds_read_b128 v[218:221], v151 offset:4096
	ds_read_b128 v[222:225], v151 offset:5120
	ds_read_b128 v[226:229], v151 offset:6144
	ds_read_b128 v[230:233], v151 offset:7168
	global_load_lds_dwordx4 v[172:173], off
	v_lshl_add_u64 v[172:173], s[28:29], 0, v[136:137]
	s_add_i32 m0, s26, 0xe000
	s_nop 0
	global_load_lds_dwordx4 v[172:173], off
	s_waitcnt vmcnt(8)
	s_waitcnt lgkmcnt(0)
	.p2alignl 3, 3212836864
	s_barrier
	v_mfma_f32_16x16x32_bf16 v[120:123], v[138:141], v[202:205], v[120:123]
	v_mfma_f32_16x16x32_bf16 v[124:127], v[156:159], v[202:205], v[124:127]
	v_mfma_f32_16x16x32_bf16 v[100:103], v[138:141], v[210:213], v[100:103]
	v_mfma_f32_16x16x32_bf16 v[104:107], v[156:159], v[210:213], v[104:107]
	v_mfma_f32_16x16x32_bf16 v[84:87], v[138:141], v[218:221], v[84:87]
	v_mfma_f32_16x16x32_bf16 v[88:91], v[156:159], v[218:221], v[88:91]
	v_mfma_f32_16x16x32_bf16 v[68:71], v[138:141], v[226:229], v[68:71]
	v_mfma_f32_16x16x32_bf16 v[72:75], v[156:159], v[226:229], v[72:75]
	v_mfma_f32_16x16x32_bf16 v[120:123], v[152:155], v[206:209], v[120:123]
	v_mfma_f32_16x16x32_bf16 v[124:127], v[160:163], v[206:209], v[124:127]
	v_mfma_f32_16x16x32_bf16 v[100:103], v[152:155], v[214:217], v[100:103]
	v_mfma_f32_16x16x32_bf16 v[104:107], v[160:163], v[214:217], v[104:107]
	v_mfma_f32_16x16x32_bf16 v[84:87], v[152:155], v[222:225], v[84:87]
	v_mfma_f32_16x16x32_bf16 v[88:91], v[160:163], v[222:225], v[88:91]
	v_mfma_f32_16x16x32_bf16 v[68:71], v[152:155], v[230:233], v[68:71]
	v_mfma_f32_16x16x32_bf16 v[72:75], v[160:163], v[230:233], v[72:75]
	v_mfma_f32_16x16x32_bf16 v[112:115], v[164:167], v[202:205], v[112:115]
	v_mfma_f32_16x16x32_bf16 v[116:119], v[180:183], v[202:205], v[116:119]
	v_mfma_f32_16x16x32_bf16 v[96:99], v[164:167], v[210:213], v[96:99]
	v_mfma_f32_16x16x32_bf16 v[108:111], v[180:183], v[210:213], v[108:111]
	v_mfma_f32_16x16x32_bf16 v[80:83], v[164:167], v[218:221], v[80:83]
	v_mfma_f32_16x16x32_bf16 v[92:95], v[180:183], v[218:221], v[92:95]
	v_mfma_f32_16x16x32_bf16 v[64:67], v[164:167], v[226:229], v[64:67]
	v_mfma_f32_16x16x32_bf16 v[76:79], v[180:183], v[226:229], v[76:79]
	v_mfma_f32_16x16x32_bf16 v[112:115], v[168:171], v[206:209], v[112:115]
	v_mfma_f32_16x16x32_bf16 v[116:119], v[198:201], v[206:209], v[116:119]
	v_mfma_f32_16x16x32_bf16 v[96:99], v[168:171], v[214:217], v[96:99]
	v_mfma_f32_16x16x32_bf16 v[108:111], v[198:201], v[214:217], v[108:111]
	v_mfma_f32_16x16x32_bf16 v[80:83], v[168:171], v[222:225], v[80:83]
	v_mfma_f32_16x16x32_bf16 v[92:95], v[198:201], v[222:225], v[92:95]
	v_mfma_f32_16x16x32_bf16 v[64:67], v[168:171], v[230:233], v[64:67]
	v_mfma_f32_16x16x32_bf16 v[76:79], v[198:201], v[230:233], v[76:79]
	s_barrier
	s_add_i32 s58, s58, s25
	v_lshl_add_u64 v[172:173], s[0:1], 0, v[144:145]
	s_mov_b32 m0, s58
	ds_read_b128 v[202:205], v151 offset:16384
	ds_read_b128 v[206:209], v151 offset:17408
	ds_read_b128 v[210:213], v151 offset:18432
	ds_read_b128 v[214:217], v151 offset:19456
	ds_read_b128 v[218:221], v151 offset:20480
	ds_read_b128 v[222:225], v151 offset:21504
	ds_read_b128 v[226:229], v151 offset:22528
	ds_read_b128 v[230:233], v151 offset:23552
	global_load_lds_dwordx4 v[172:173], off
	s_add_i32 m0, s58, 0x2000
	s_add_u32 s58, s0, 0x40000
	v_lshl_add_u64 v[184:185], s[0:1], 0, v[128:129]
	s_addc_u32 s59, s1, 0
	s_add_i32 s60, s60, s25
	global_load_lds_dwordx4 v[184:185], off
	v_lshl_add_u64 v[186:187], s[58:59], 0, v[144:145]
	s_mov_b32 m0, s60
	v_lshl_add_u64 v[188:189], s[6:7], 0, v[130:131]
	global_load_lds_dwordx4 v[186:187], off
	v_lshl_add_u64 v[186:187], s[58:59], 0, v[128:129]
	s_add_i32 m0, s60, 0x2000
	s_nop 0
	global_load_lds_dwordx4 v[186:187], off
	v_lshl_add_u64 v[186:187], s[6:7], 0, v[132:133]
	s_mov_b32 m0, s26
	s_nop 0
	global_load_lds_dwordx4 v[186:187], off
	s_mov_b32 m0, s27
	s_nop 0
	global_load_lds_dwordx4 v[188:189], off
	s_waitcnt vmcnt(8)
	s_waitcnt lgkmcnt(0)
	.p2alignl 3, 3212836864
	s_barrier
; #define PG8_STAGE(bufoff, gbase, voff) do { _Pragma("unroll") for (int _i = 0; _i < 2; ++_i) \
;         __builtin_amdgcn_global_load_lds((const unsigned*)((const char*)(gbase) + (voff)[_i]), (PG8_LAS unsigned*)(lds + (bufoff) + ldsw + _i * 8192), 16, 0, 0); } while (0)
; #define PG8_LDA(dst, b, h) do { _Pragma("unroll") for (int m = 0; m < 4; ++m) _Pragma("unroll") for (int k = 0; k < 2; ++k) dst[m][k] = *(const PG8_LAS bf16x8*)(lds + PG8_SA(b, h) + aoff + m * 2048 + k * 1024); } while (0)
; #define PG8_LDB(dst, b, h) do { _Pragma("unroll") for (int n = 0; n < 2; ++n) _Pragma("unroll") for (int k = 0; k < 2; ++k) dst[n][k] = *(const PG8_LAS bf16x8*)(lds + PG8_SB(b, h) + boff + n * 2048 + k * 1024); } while (0)
; #define PG8_MMA(ai, bj, At, Bt) do { __builtin_amdgcn_s_setprio(1); _Pragma("unroll") for (int m = 0; m < 4; ++m) _Pragma("unroll") for (int n = 0; n < 2; ++n) _Pragma("unroll") for (int k = 0; k < 2; ++k) \
;         acc[ai][bj][m][n] = __builtin_amdgcn_mfma_f32_16x16x32_bf16(Bt[n][k], At[m][k], acc[ai][bj][m][n], 0, 0, 0); __builtin_amdgcn_s_setprio(0); } while (0)
; #define PG8_WAIT_V(n) asm volatile("s_waitcnt vmcnt(" #n ")" ::: "memory")
; #define PG8_WAIT_L(n) asm volatile("s_waitcnt lgkmcnt(" #n ")" ::: "memory")
; #define PG8_BAR __builtin_amdgcn_s_barrier()
; #define PG8_SCHED __builtin_amdgcn_sched_barrier(0)
; template <class Epi, class Sched, bool ALIGN_EPI = false, bool SP2 = false>
; __device__ __forceinline__ void gemm_phase(PG8_LAS unsigned char* lds, const Gemm g, const Sched& S, const Epi& E) {
;     ...
;             PG8_WAIT_V(8); PG8_WAIT_L(0); PG8_BAR; PG8_MMA(1, 0, At, B0); PG8_MMA(1, 1, At, B1); PG8_BAR; PG8_SCHED;
;             PG8_LDB(B0, 1, 0); PG8_LDB(B1, 1, 1); PG8_SCHED; PG8_LDA(At, 1, 0); PG8_STAGE(PG8_SA(0, 1), a2 + hstep, voffA);
;             PG8_WAIT_V(8); PG8_WAIT_L(0); PG8_BAR; PG8_MMA(0, 0, At, B0); PG8_MMA(0, 1, At, B1); PG8_BAR; PG8_SCHED;
	v_mfma_f32_16x16x32_bf16 v[52:55], v[138:141], v[202:205], v[52:55]
	v_mfma_f32_16x16x32_bf16 v[56:59], v[156:159], v[202:205], v[56:59]
	v_mfma_f32_16x16x32_bf16 v[36:39], v[138:141], v[210:213], v[36:39]
	v_mfma_f32_16x16x32_bf16 v[40:43], v[156:159], v[210:213], v[40:43]
	v_mfma_f32_16x16x32_bf16 v[20:23], v[138:141], v[218:221], v[20:23]
	v_mfma_f32_16x16x32_bf16 v[24:27], v[156:159], v[218:221], v[24:27]
	v_mfma_f32_16x16x32_bf16 v[4:7], v[138:141], v[226:229], v[4:7]
	v_mfma_f32_16x16x32_bf16 v[8:11], v[156:159], v[226:229], v[8:11]
	v_mfma_f32_16x16x32_bf16 v[52:55], v[152:155], v[206:209], v[52:55]
	v_mfma_f32_16x16x32_bf16 v[56:59], v[160:163], v[206:209], v[56:59]
	v_mfma_f32_16x16x32_bf16 v[36:39], v[152:155], v[214:217], v[36:39]
	v_mfma_f32_16x16x32_bf16 v[40:43], v[160:163], v[214:217], v[40:43]
	v_mfma_f32_16x16x32_bf16 v[20:23], v[152:155], v[222:225], v[20:23]
	v_mfma_f32_16x16x32_bf16 v[24:27], v[160:163], v[222:225], v[24:27]
	v_mfma_f32_16x16x32_bf16 v[4:7], v[152:155], v[230:233], v[4:7]
	v_mfma_f32_16x16x32_bf16 v[8:11], v[160:163], v[230:233], v[8:11]
	v_mfma_f32_16x16x32_bf16 v[48:51], v[164:167], v[202:205], v[48:51]
	v_mfma_f32_16x16x32_bf16 v[60:63], v[180:183], v[202:205], v[60:63]
	v_mfma_f32_16x16x32_bf16 v[32:35], v[164:167], v[210:213], v[32:35]
	v_mfma_f32_16x16x32_bf16 v[44:47], v[180:183], v[210:213], v[44:47]
	v_mfma_f32_16x16x32_bf16 v[16:19], v[164:167], v[218:221], v[16:19]
	v_mfma_f32_16x16x32_bf16 v[28:31], v[180:183], v[218:221], v[28:31]
	v_mfma_f32_16x16x32_bf16 v[0:3], v[164:167], v[226:229], v[0:3]
	v_mfma_f32_16x16x32_bf16 v[12:15], v[180:183], v[226:229], v[12:15]
	v_mfma_f32_16x16x32_bf16 v[48:51], v[168:171], v[206:209], v[48:51]
	v_mfma_f32_16x16x32_bf16 v[60:63], v[198:201], v[206:209], v[60:63]
	v_mfma_f32_16x16x32_bf16 v[32:35], v[168:171], v[214:217], v[32:35]
	v_mfma_f32_16x16x32_bf16 v[44:47], v[198:201], v[214:217], v[44:47]
	v_mfma_f32_16x16x32_bf16 v[16:19], v[168:171], v[222:225], v[16:19]
	v_mfma_f32_16x16x32_bf16 v[28:31], v[198:201], v[222:225], v[28:31]
	v_mfma_f32_16x16x32_bf16 v[0:3], v[168:171], v[230:233], v[0:3]
	v_mfma_f32_16x16x32_bf16 v[12:15], v[198:201], v[230:233], v[12:15]
	s_barrier
	s_add_i32 s58, 0, 0x18000
	s_add_i32 s59, 0, 0x1c000
	v_add_u32_e32 v160, s58, v143
	v_add_u32_e32 v190, s59, v143
	ds_read_b128 v[138:141], v160
	ds_read_b128 v[152:155], v160 offset:1024
	ds_read_b128 v[156:159], v160 offset:2048
	ds_read_b128 v[160:163], v160 offset:3072
	ds_read_b128 v[164:167], v190
	ds_read_b128 v[168:171], v190 offset:1024
	ds_read_b128 v[180:183], v190 offset:2048
	ds_read_b128 v[198:201], v190 offset:3072
	s_add_u32 s6, s6, 0x40000
	s_addc_u32 s7, s7, 0
	s_mov_b32 m0, s30
	v_lshl_add_u64 v[190:191], s[6:7], 0, v[132:133]
	ds_read_b128 v[202:205], v151 offset:32768
	ds_read_b128 v[206:209], v151 offset:33792
	ds_read_b128 v[210:213], v151 offset:34816
	ds_read_b128 v[214:217], v151 offset:35840
	ds_read_b128 v[218:221], v151 offset:36864
	ds_read_b128 v[222:225], v151 offset:37888
	ds_read_b128 v[226:229], v151 offset:38912
	ds_read_b128 v[230:233], v151 offset:39936
	global_load_lds_dwordx4 v[190:191], off
	v_lshl_add_u64 v[190:191], s[6:7], 0, v[130:131]
	s_mov_b32 m0, s31
	s_nop 0
	global_load_lds_dwordx4 v[190:191], off
	s_waitcnt vmcnt(8)
	s_waitcnt lgkmcnt(0)
	.p2alignl 3, 3212836864
	s_barrier
	v_mfma_f32_16x16x32_bf16 v[120:123], v[138:141], v[202:205], v[120:123]
	v_mfma_f32_16x16x32_bf16 v[124:127], v[156:159], v[202:205], v[124:127]
	v_mfma_f32_16x16x32_bf16 v[100:103], v[138:141], v[210:213], v[100:103]
	v_mfma_f32_16x16x32_bf16 v[104:107], v[156:159], v[210:213], v[104:107]
	v_mfma_f32_16x16x32_bf16 v[84:87], v[138:141], v[218:221], v[84:87]
	v_mfma_f32_16x16x32_bf16 v[88:91], v[156:159], v[218:221], v[88:91]
	v_mfma_f32_16x16x32_bf16 v[68:71], v[138:141], v[226:229], v[68:71]
	v_mfma_f32_16x16x32_bf16 v[72:75], v[156:159], v[226:229], v[72:75]
	v_mfma_f32_16x16x32_bf16 v[120:123], v[152:155], v[206:209], v[120:123]
	v_mfma_f32_16x16x32_bf16 v[124:127], v[160:163], v[206:209], v[124:127]
	v_mfma_f32_16x16x32_bf16 v[100:103], v[152:155], v[214:217], v[100:103]
	v_mfma_f32_16x16x32_bf16 v[104:107], v[160:163], v[214:217], v[104:107]
	v_mfma_f32_16x16x32_bf16 v[84:87], v[152:155], v[222:225], v[84:87]
	v_mfma_f32_16x16x32_bf16 v[88:91], v[160:163], v[222:225], v[88:91]
	v_mfma_f32_16x16x32_bf16 v[68:71], v[152:155], v[230:233], v[68:71]
	v_mfma_f32_16x16x32_bf16 v[72:75], v[160:163], v[230:233], v[72:75]
	v_mfma_f32_16x16x32_bf16 v[112:115], v[164:167], v[202:205], v[112:115]
	v_mfma_f32_16x16x32_bf16 v[116:119], v[180:183], v[202:205], v[116:119]
	v_mfma_f32_16x16x32_bf16 v[96:99], v[164:167], v[210:213], v[96:99]
	v_mfma_f32_16x16x32_bf16 v[108:111], v[180:183], v[210:213], v[108:111]
	v_mfma_f32_16x16x32_bf16 v[80:83], v[164:167], v[218:221], v[80:83]
	v_mfma_f32_16x16x32_bf16 v[92:95], v[180:183], v[218:221], v[92:95]
	v_mfma_f32_16x16x32_bf16 v[64:67], v[164:167], v[226:229], v[64:67]
	v_mfma_f32_16x16x32_bf16 v[76:79], v[180:183], v[226:229], v[76:79]
	v_mfma_f32_16x16x32_bf16 v[112:115], v[168:171], v[206:209], v[112:115]
	v_mfma_f32_16x16x32_bf16 v[116:119], v[198:201], v[206:209], v[116:119]
	v_mfma_f32_16x16x32_bf16 v[96:99], v[168:171], v[214:217], v[96:99]
	v_mfma_f32_16x16x32_bf16 v[108:111], v[198:201], v[214:217], v[108:111]
	v_mfma_f32_16x16x32_bf16 v[80:83], v[168:171], v[222:225], v[80:83]
	v_mfma_f32_16x16x32_bf16 v[92:95], v[198:201], v[222:225], v[92:95]
	v_mfma_f32_16x16x32_bf16 v[64:67], v[168:171], v[230:233], v[64:67]
	v_mfma_f32_16x16x32_bf16 v[76:79], v[198:201], v[230:233], v[76:79]
	s_barrier
; #define PG8_STAGE(bufoff, gbase, voff) do { _Pragma("unroll") for (int _i = 0; _i < 2; ++_i) \
;         __builtin_amdgcn_global_load_lds((const unsigned*)((const char*)(gbase) + (voff)[_i]), (PG8_LAS unsigned*)(lds + (bufoff) + ldsw + _i * 8192), 16, 0, 0); } while (0)
; #define PG8_LDA(dst, b, h) do { _Pragma("unroll") for (int m = 0; m < 4; ++m) _Pragma("unroll") for (int k = 0; k < 2; ++k) dst[m][k] = *(const PG8_LAS bf16x8*)(lds + PG8_SA(b, h) + aoff + m * 2048 + k * 1024); } while (0)
; #define PG8_MMA(ai, bj, At, Bt) do { __builtin_amdgcn_s_setprio(1); _Pragma("unroll") for (int m = 0; m < 4; ++m) _Pragma("unroll") for (int n = 0; n < 2; ++n) _Pragma("unroll") for (int k = 0; k < 2; ++k) \
;         acc[ai][bj][m][n] = __builtin_amdgcn_mfma_f32_16x16x32_bf16(Bt[n][k], At[m][k], acc[ai][bj][m][n], 0, 0, 0); __builtin_amdgcn_s_setprio(0); } while (0)
; #define PG8_WAIT_V(n) asm volatile("s_waitcnt vmcnt(" #n ")" ::: "memory")
; #define PG8_WAIT_L(n) asm volatile("s_waitcnt lgkmcnt(" #n ")" ::: "memory")
; #define PG8_BAR __builtin_amdgcn_s_barrier()
; #define PG8_SCHED __builtin_amdgcn_sched_barrier(0)
; template <class Epi, class Sched, bool ALIGN_EPI = false, bool SP2 = false>
; __device__ __forceinline__ void gemm_phase(PG8_LAS unsigned char* lds, const Gemm g, const Sched& S, const Epi& E) {
;     ...
;             PG8_LDA(At, 1, 1); PG8_STAGE(PG8_SB(1, 0), b3, voffB); PG8_STAGE(PG8_SB(1, 1), b3 + hstep, voffB); PG8_STAGE(PG8_SA(1, 0), a3, voffA);
;             PG8_WAIT_V(8); PG8_WAIT_L(0); PG8_BAR; PG8_MMA(1, 0, At, B0); PG8_MMA(1, 1, At, B1); PG8_BAR; PG8_SCHED;
;     ...
;         if constexpr (ALIGN_EPI) { if (wr == 0) PG8_BAR; }
	s_add_i32 s6, s58, s25
	v_lshl_add_u64 v[172:173], v[172:173], 0, s[94:95]
	s_mov_b32 m0, s6
	ds_read_b128 v[202:205], v151 offset:49152
	ds_read_b128 v[206:209], v151 offset:50176
	ds_read_b128 v[210:213], v151 offset:51200
	ds_read_b128 v[214:217], v151 offset:52224
	ds_read_b128 v[218:221], v151 offset:53248
	ds_read_b128 v[222:225], v151 offset:54272
	ds_read_b128 v[226:229], v151 offset:55296
	ds_read_b128 v[230:233], v151 offset:56320
	global_load_lds_dwordx4 v[172:173], off
	s_add_i32 m0, s6, 0x2000
	s_add_u32 s0, s0, 0x40080
	v_lshl_add_u64 v[172:173], v[184:185], 0, s[94:95]
	s_addc_u32 s1, s1, 0
	s_add_i32 s6, s59, s25
	global_load_lds_dwordx4 v[172:173], off
	v_lshl_add_u64 v[172:173], s[0:1], 0, v[144:145]
	s_mov_b32 m0, s6
	s_nop 0
	global_load_lds_dwordx4 v[172:173], off
	v_lshl_add_u64 v[172:173], s[0:1], 0, v[128:129]
	s_add_i32 m0, s6, 0x2000
	s_nop 0
	global_load_lds_dwordx4 v[172:173], off
	v_lshl_add_u64 v[172:173], v[186:187], 0, s[94:95]
	s_mov_b32 m0, s34
	s_nop 0
	global_load_lds_dwordx4 v[172:173], off
	v_lshl_add_u64 v[172:173], v[188:189], 0, s[94:95]
	s_mov_b32 m0, s35
	s_nop 0
	global_load_lds_dwordx4 v[172:173], off
	s_waitcnt vmcnt(8)
	s_waitcnt lgkmcnt(0)
	.p2alignl 3, 3212836864
	s_barrier
	v_mfma_f32_16x16x32_bf16 v[52:55], v[138:141], v[202:205], v[52:55]
	v_mfma_f32_16x16x32_bf16 v[56:59], v[156:159], v[202:205], v[56:59]
	v_mfma_f32_16x16x32_bf16 v[36:39], v[138:141], v[210:213], v[36:39]
	v_mfma_f32_16x16x32_bf16 v[40:43], v[156:159], v[210:213], v[40:43]
	v_mfma_f32_16x16x32_bf16 v[20:23], v[138:141], v[218:221], v[20:23]
	v_mfma_f32_16x16x32_bf16 v[24:27], v[156:159], v[218:221], v[24:27]
	v_mfma_f32_16x16x32_bf16 v[4:7], v[138:141], v[226:229], v[4:7]
	v_mfma_f32_16x16x32_bf16 v[8:11], v[156:159], v[226:229], v[8:11]
	v_mfma_f32_16x16x32_bf16 v[52:55], v[152:155], v[206:209], v[52:55]
	v_mfma_f32_16x16x32_bf16 v[56:59], v[160:163], v[206:209], v[56:59]
	v_mfma_f32_16x16x32_bf16 v[36:39], v[152:155], v[214:217], v[36:39]
	v_mfma_f32_16x16x32_bf16 v[40:43], v[160:163], v[214:217], v[40:43]
	v_mfma_f32_16x16x32_bf16 v[20:23], v[152:155], v[222:225], v[20:23]
	v_mfma_f32_16x16x32_bf16 v[24:27], v[160:163], v[222:225], v[24:27]
	v_mfma_f32_16x16x32_bf16 v[4:7], v[152:155], v[230:233], v[4:7]
	v_mfma_f32_16x16x32_bf16 v[8:11], v[160:163], v[230:233], v[8:11]
	v_mfma_f32_16x16x32_bf16 v[48:51], v[164:167], v[202:205], v[48:51]
	v_mfma_f32_16x16x32_bf16 v[60:63], v[180:183], v[202:205], v[60:63]
	v_mfma_f32_16x16x32_bf16 v[32:35], v[164:167], v[210:213], v[32:35]
	v_mfma_f32_16x16x32_bf16 v[44:47], v[180:183], v[210:213], v[44:47]
	v_mfma_f32_16x16x32_bf16 v[16:19], v[164:167], v[218:221], v[16:19]
	v_mfma_f32_16x16x32_bf16 v[28:31], v[180:183], v[218:221], v[28:31]
	v_mfma_f32_16x16x32_bf16 v[0:3], v[164:167], v[226:229], v[0:3]
	v_mfma_f32_16x16x32_bf16 v[12:15], v[180:183], v[226:229], v[12:15]
	v_mfma_f32_16x16x32_bf16 v[48:51], v[168:171], v[206:209], v[48:51]
	v_mfma_f32_16x16x32_bf16 v[60:63], v[198:201], v[206:209], v[60:63]
	v_mfma_f32_16x16x32_bf16 v[32:35], v[168:171], v[214:217], v[32:35]
	v_mfma_f32_16x16x32_bf16 v[44:47], v[198:201], v[214:217], v[44:47]
	v_mfma_f32_16x16x32_bf16 v[16:19], v[168:171], v[222:225], v[16:19]
	v_mfma_f32_16x16x32_bf16 v[28:31], v[198:201], v[222:225], v[28:31]
	v_mfma_f32_16x16x32_bf16 v[0:3], v[168:171], v[230:233], v[0:3]
	v_mfma_f32_16x16x32_bf16 v[12:15], v[198:201], v[230:233], v[12:15]
	s_barrier
	s_add_i32 s57, s57, 2
	s_add_u32 s28, s28, 0x100
	s_addc_u32 s29, s29, 0
	s_add_u32 s55, s55, 0x100
	s_addc_u32 s56, s56, 0
	s_cmp_gt_u32 s57, 13
	s_cbranch_scc0 .LBB0_1562
	s_and_b64 vcc, exec, s[42:43]
	s_cbranch_vccz .LBB0_1565
	s_barrier

; #define PG8_STAGE(bufoff, gbase, voff) do { _Pragma("unroll") for (int _i = 0; _i < 2; ++_i) \
;         __builtin_amdgcn_global_load_lds((const unsigned*)((const char*)(gbase) + (voff)[_i]), (PG8_LAS unsigned*)(lds + (bufoff) + ldsw + _i * 8192), 16, 0, 0); } while (0)
; #define PG8_LDA(dst, b, h) do { _Pragma("unroll") for (int m = 0; m < 4; ++m) _Pragma("unroll") for (int k = 0; k < 2; ++k) dst[m][k] = *(const PG8_LAS bf16x8*)(lds + PG8_SA(b, h) + aoff + m * 2048 + k * 1024); } while (0)
; #define PG8_MMA(ai, bj, At, Bt) do { __builtin_amdgcn_s_setprio(1); _Pragma("unroll") for (int m = 0; m < 4; ++m) _Pragma("unroll") for (int n = 0; n < 2; ++n) _Pragma("unroll") for (int k = 0; k < 2; ++k) \
;         acc[ai][bj][m][n] = __builtin_amdgcn_mfma_f32_16x16x32_bf16(Bt[n][k], At[m][k], acc[ai][bj][m][n], 0, 0, 0); __builtin_amdgcn_s_setprio(0); } while (0)
; #define PG8_WAIT_V(n) asm volatile("s_waitcnt vmcnt(" #n ")" ::: "memory")
; #define PG8_WAIT_L(n) asm volatile("s_waitcnt lgkmcnt(" #n ")" ::: "memory")
; #define PG8_BAR __builtin_amdgcn_s_barrier()
; #define PG8_SCHED __builtin_amdgcn_sched_barrier(0)
; template <class Epi, class Sched, bool ALIGN_EPI = false, bool SP2 = false>
; __device__ __forceinline__ void gemm_phase(PG8_LAS unsigned char* lds, const Gemm g, const Sched& S, const Epi& E) {
;     ...
;             PG8_WAIT_V(8); PG8_WAIT_L(0); PG8_BAR; PG8_MMA(0, 0, At, B0); PG8_MMA(0, 1, At, B1); PG8_BAR; PG8_SCHED;
;             PG8_LDA(At, 0, 1); PG8_STAGE(PG8_SB(0, 0), b2, voffB); PG8_STAGE(PG8_SB(0, 1), b2 + hstep, voffB); PG8_STAGE(PG8_SA(0, 0), a2, voffA);
;             PG8_WAIT_V(8); PG8_WAIT_L(0); PG8_BAR; PG8_MMA(1, 0, At, B0); PG8_MMA(1, 1, At, B1); PG8_BAR; PG8_SCHED;
.Lgu_relaxed0:
	s_waitcnt lgkmcnt(0)
	.p2alignl 3, 3212836864
	s_barrier
	v_mfma_f32_16x16x32_bf16 v[124:127], v[132:135], v[216:219], v[124:127]
	v_mfma_f32_16x16x32_bf16 v[116:119], v[140:143], v[216:219], v[116:119]
	v_mfma_f32_16x16x32_bf16 v[108:111], v[132:135], v[224:227], v[108:111]
	v_mfma_f32_16x16x32_bf16 v[100:103], v[140:143], v[224:227], v[100:103]
	v_mfma_f32_16x16x32_bf16 v[92:95], v[132:135], v[232:235], v[92:95]
	v_mfma_f32_16x16x32_bf16 v[84:87], v[140:143], v[232:235], v[84:87]
	v_mfma_f32_16x16x32_bf16 v[76:79], v[132:135], v[240:243], v[76:79]
	v_mfma_f32_16x16x32_bf16 v[68:71], v[140:143], v[240:243], v[68:71]
	v_mfma_f32_16x16x32_bf16 v[124:127], v[136:139], v[220:223], v[124:127]
	v_mfma_f32_16x16x32_bf16 v[116:119], v[180:183], v[220:223], v[116:119]
	v_mfma_f32_16x16x32_bf16 v[108:111], v[136:139], v[228:231], v[108:111]
	v_mfma_f32_16x16x32_bf16 v[100:103], v[180:183], v[228:231], v[100:103]
	v_mfma_f32_16x16x32_bf16 v[92:95], v[136:139], v[236:239], v[92:95]
	v_mfma_f32_16x16x32_bf16 v[84:87], v[180:183], v[236:239], v[84:87]
	v_mfma_f32_16x16x32_bf16 v[76:79], v[136:139], v[244:247], v[76:79]
	v_mfma_f32_16x16x32_bf16 v[68:71], v[180:183], v[244:247], v[68:71]
	v_mfma_f32_16x16x32_bf16 v[120:123], v[200:203], v[216:219], v[120:123]
	v_mfma_f32_16x16x32_bf16 v[112:115], v[208:211], v[216:219], v[112:115]
	v_mfma_f32_16x16x32_bf16 v[104:107], v[200:203], v[224:227], v[104:107]
	v_mfma_f32_16x16x32_bf16 v[96:99], v[208:211], v[224:227], v[96:99]
	v_mfma_f32_16x16x32_bf16 v[88:91], v[200:203], v[232:235], v[88:91]
	v_mfma_f32_16x16x32_bf16 v[80:83], v[208:211], v[232:235], v[80:83]
	v_mfma_f32_16x16x32_bf16 v[72:75], v[200:203], v[240:243], v[72:75]
	v_mfma_f32_16x16x32_bf16 v[64:67], v[208:211], v[240:243], v[64:67]
	v_mfma_f32_16x16x32_bf16 v[120:123], v[204:207], v[220:223], v[120:123]
	v_mfma_f32_16x16x32_bf16 v[112:115], v[212:215], v[220:223], v[112:115]
	v_mfma_f32_16x16x32_bf16 v[104:107], v[204:207], v[228:231], v[104:107]
	v_mfma_f32_16x16x32_bf16 v[96:99], v[212:215], v[228:231], v[96:99]
	v_mfma_f32_16x16x32_bf16 v[88:91], v[204:207], v[236:239], v[88:91]
	v_mfma_f32_16x16x32_bf16 v[80:83], v[212:215], v[236:239], v[80:83]
	v_mfma_f32_16x16x32_bf16 v[72:75], v[204:207], v[244:247], v[72:75]
	v_mfma_f32_16x16x32_bf16 v[64:67], v[212:215], v[244:247], v[64:67]
	s_barrier
	s_add_i32 s58, s58, s26
	v_lshl_add_u64 v[168:169], s[0:1], 0, v[144:145]
	s_mov_b32 m0, s58
	ds_read_b128 v[216:219], v197 offset:16384
	ds_read_b128 v[220:223], v197 offset:17408
	ds_read_b128 v[224:227], v197 offset:18432
	ds_read_b128 v[228:231], v197 offset:19456
	ds_read_b128 v[232:235], v197 offset:20480
	ds_read_b128 v[236:239], v197 offset:21504
	ds_read_b128 v[240:243], v197 offset:22528
	ds_read_b128 v[244:247], v197 offset:23552
	global_load_lds_dwordx4 v[168:169], off
	s_add_i32 m0, s58, 0x2000
	s_add_u32 s58, s0, 0x40000
	v_lshl_add_u64 v[172:173], s[0:1], 0, v[150:151]
	s_addc_u32 s59, s1, 0
	s_add_i32 s60, s60, s26
	global_load_lds_dwordx4 v[172:173], off
	v_lshl_add_u64 v[184:185], s[58:59], 0, v[144:145]
	s_mov_b32 m0, s60
	v_lshl_add_u64 v[186:187], s[6:7], 0, v[152:153]
	global_load_lds_dwordx4 v[184:185], off
	v_lshl_add_u64 v[184:185], s[58:59], 0, v[150:151]
	s_add_i32 m0, s60, 0x2000
	s_nop 0
	global_load_lds_dwordx4 v[184:185], off
	v_lshl_add_u64 v[184:185], s[6:7], 0, v[154:155]
	s_mov_b32 m0, s27
	s_nop 0
	global_load_lds_dwordx4 v[184:185], off
	s_mov_b32 m0, s28
	s_nop 0
	global_load_lds_dwordx4 v[186:187], off
	s_waitcnt vmcnt(16)
	s_cmp_lg_u32 vcc_lo, 0
	s_cbranch_scc1 .Lgu_relaxed1
	s_waitcnt vmcnt(8)
.Lgu_relaxed1:
	s_waitcnt lgkmcnt(0)
	.p2alignl 3, 3212836864
	s_barrier
	v_mfma_f32_16x16x32_bf16 v[60:63], v[132:135], v[216:219], v[60:63]
	v_mfma_f32_16x16x32_bf16 v[52:55], v[140:143], v[216:219], v[52:55]
	v_mfma_f32_16x16x32_bf16 v[44:47], v[132:135], v[224:227], v[44:47]
	v_mfma_f32_16x16x32_bf16 v[36:39], v[140:143], v[224:227], v[36:39]
	v_mfma_f32_16x16x32_bf16 v[28:31], v[132:135], v[232:235], v[28:31]
	v_mfma_f32_16x16x32_bf16 v[20:23], v[140:143], v[232:235], v[20:23]
	v_mfma_f32_16x16x32_bf16 v[12:15], v[132:135], v[240:243], v[12:15]
	v_mfma_f32_16x16x32_bf16 v[4:7], v[140:143], v[240:243], v[4:7]
	v_mfma_f32_16x16x32_bf16 v[60:63], v[136:139], v[220:223], v[60:63]
	v_mfma_f32_16x16x32_bf16 v[52:55], v[180:183], v[220:223], v[52:55]
	v_mfma_f32_16x16x32_bf16 v[44:47], v[136:139], v[228:231], v[44:47]
	v_mfma_f32_16x16x32_bf16 v[36:39], v[180:183], v[228:231], v[36:39]
	v_mfma_f32_16x16x32_bf16 v[28:31], v[136:139], v[236:239], v[28:31]
	v_mfma_f32_16x16x32_bf16 v[20:23], v[180:183], v[236:239], v[20:23]
	v_mfma_f32_16x16x32_bf16 v[12:15], v[136:139], v[244:247], v[12:15]
	v_mfma_f32_16x16x32_bf16 v[4:7], v[180:183], v[244:247], v[4:7]
	v_mfma_f32_16x16x32_bf16 v[56:59], v[200:203], v[216:219], v[56:59]
	v_mfma_f32_16x16x32_bf16 v[48:51], v[208:211], v[216:219], v[48:51]
	v_mfma_f32_16x16x32_bf16 v[40:43], v[200:203], v[224:227], v[40:43]
	v_mfma_f32_16x16x32_bf16 v[32:35], v[208:211], v[224:227], v[32:35]
	v_mfma_f32_16x16x32_bf16 v[24:27], v[200:203], v[232:235], v[24:27]
	v_mfma_f32_16x16x32_bf16 v[16:19], v[208:211], v[232:235], v[16:19]
	v_mfma_f32_16x16x32_bf16 v[8:11], v[200:203], v[240:243], v[8:11]
	v_mfma_f32_16x16x32_bf16 v[0:3], v[208:211], v[240:243], v[0:3]
	v_mfma_f32_16x16x32_bf16 v[56:59], v[204:207], v[220:223], v[56:59]
	v_mfma_f32_16x16x32_bf16 v[48:51], v[212:215], v[220:223], v[48:51]
	v_mfma_f32_16x16x32_bf16 v[40:43], v[204:207], v[228:231], v[40:43]
	v_mfma_f32_16x16x32_bf16 v[32:35], v[212:215], v[228:231], v[32:35]
	v_mfma_f32_16x16x32_bf16 v[24:27], v[204:207], v[236:239], v[24:27]
	v_mfma_f32_16x16x32_bf16 v[16:19], v[212:215], v[236:239], v[16:19]
	v_mfma_f32_16x16x32_bf16 v[8:11], v[204:207], v[244:247], v[8:11]
	v_mfma_f32_16x16x32_bf16 v[0:3], v[212:215], v[244:247], v[0:3]
	s_barrier
; #define PG8_STAGE(bufoff, gbase, voff) do { _Pragma("unroll") for (int _i = 0; _i < 2; ++_i) \
;         __builtin_amdgcn_global_load_lds((const unsigned*)((const char*)(gbase) + (voff)[_i]), (PG8_LAS unsigned*)(lds + (bufoff) + ldsw + _i * 8192), 16, 0, 0); } while (0)
; #define PG8_LDA(dst, b, h) do { _Pragma("unroll") for (int m = 0; m < 4; ++m) _Pragma("unroll") for (int k = 0; k < 2; ++k) dst[m][k] = *(const PG8_LAS bf16x8*)(lds + PG8_SA(b, h) + aoff + m * 2048 + k * 1024); } while (0)
; #define PG8_LDB(dst, b, h) do { _Pragma("unroll") for (int n = 0; n < 2; ++n) _Pragma("unroll") for (int k = 0; k < 2; ++k) dst[n][k] = *(const PG8_LAS bf16x8*)(lds + PG8_SB(b, h) + boff + n * 2048 + k * 1024); } while (0)
; #define PG8_MMA(ai, bj, At, Bt) do { __builtin_amdgcn_s_setprio(1); _Pragma("unroll") for (int m = 0; m < 4; ++m) _Pragma("unroll") for (int n = 0; n < 2; ++n) _Pragma("unroll") for (int k = 0; k < 2; ++k) \
;         acc[ai][bj][m][n] = __builtin_amdgcn_mfma_f32_16x16x32_bf16(Bt[n][k], At[m][k], acc[ai][bj][m][n], 0, 0, 0); __builtin_amdgcn_s_setprio(0); } while (0)
; #define PG8_WAIT_V(n) asm volatile("s_waitcnt vmcnt(" #n ")" ::: "memory")
; #define PG8_WAIT_L(n) asm volatile("s_waitcnt lgkmcnt(" #n ")" ::: "memory")
; #define PG8_BAR __builtin_amdgcn_s_barrier()
; #define PG8_SCHED __builtin_amdgcn_sched_barrier(0)
; template <class Epi, class Sched, bool ALIGN_EPI = false, bool SP2 = false>
; __device__ __forceinline__ void gemm_phase(PG8_LAS unsigned char* lds, const Gemm g, const Sched& S, const Epi& E) {
;     ...
;             PG8_LDB(B0, 1, 0); PG8_LDB(B1, 1, 1); PG8_SCHED; PG8_LDA(At, 1, 0); PG8_STAGE(PG8_SA(0, 1), a2 + hstep, voffA);
;             PG8_WAIT_V(8); PG8_WAIT_L(0); PG8_BAR; PG8_MMA(0, 0, At, B0); PG8_MMA(0, 1, At, B1); PG8_BAR; PG8_SCHED;
;             PG8_LDA(At, 1, 1); PG8_STAGE(PG8_SB(1, 0), b3, voffB); PG8_STAGE(PG8_SB(1, 1), b3 + hstep, voffB); PG8_STAGE(PG8_SA(1, 0), a3, voffA);
;             PG8_WAIT_V(8); PG8_WAIT_L(0); PG8_BAR; PG8_MMA(1, 0, At, B0); PG8_MMA(1, 1, At, B1); PG8_BAR; PG8_SCHED;
	s_add_i32 s58, 0, 0x18000
	v_add_u32_e32 v162, s58, v165
	s_add_i32 s59, 0, 0x1c000
	ds_read_b128 v[132:135], v162
	ds_read_b128 v[136:139], v162 offset:1024
	ds_read_b128 v[140:143], v162 offset:2048
	ds_read_b128 v[180:183], v162 offset:3072
	v_add_u32_e32 v162, s59, v165
	ds_read_b128 v[200:203], v162
	ds_read_b128 v[204:207], v162 offset:1024
	ds_read_b128 v[208:211], v162 offset:2048
	ds_read_b128 v[212:215], v162 offset:3072
	s_add_u32 s6, s6, 0x40000
	s_addc_u32 s7, s7, 0
	s_mov_b32 m0, s29
	v_lshl_add_u64 v[188:189], s[6:7], 0, v[154:155]
	ds_read_b128 v[216:219], v197 offset:32768
	ds_read_b128 v[220:223], v197 offset:33792
	ds_read_b128 v[224:227], v197 offset:34816
	ds_read_b128 v[228:231], v197 offset:35840
	ds_read_b128 v[232:235], v197 offset:36864
	ds_read_b128 v[236:239], v197 offset:37888
	ds_read_b128 v[240:243], v197 offset:38912
	ds_read_b128 v[244:247], v197 offset:39936
	global_load_lds_dwordx4 v[188:189], off
	v_lshl_add_u64 v[188:189], s[6:7], 0, v[152:153]
	s_mov_b32 m0, s30
	s_nop 0
	global_load_lds_dwordx4 v[188:189], off
	s_waitcnt vmcnt(8)
	s_waitcnt lgkmcnt(0)
	.p2alignl 3, 3212836864
	s_barrier
	v_mfma_f32_16x16x32_bf16 v[124:127], v[132:135], v[216:219], v[124:127]
	v_mfma_f32_16x16x32_bf16 v[116:119], v[140:143], v[216:219], v[116:119]
	v_mfma_f32_16x16x32_bf16 v[108:111], v[132:135], v[224:227], v[108:111]
	v_mfma_f32_16x16x32_bf16 v[100:103], v[140:143], v[224:227], v[100:103]
	v_mfma_f32_16x16x32_bf16 v[92:95], v[132:135], v[232:235], v[92:95]
	v_mfma_f32_16x16x32_bf16 v[84:87], v[140:143], v[232:235], v[84:87]
	v_mfma_f32_16x16x32_bf16 v[76:79], v[132:135], v[240:243], v[76:79]
	v_mfma_f32_16x16x32_bf16 v[68:71], v[140:143], v[240:243], v[68:71]
	v_mfma_f32_16x16x32_bf16 v[124:127], v[136:139], v[220:223], v[124:127]
	v_mfma_f32_16x16x32_bf16 v[116:119], v[180:183], v[220:223], v[116:119]
	v_mfma_f32_16x16x32_bf16 v[108:111], v[136:139], v[228:231], v[108:111]
	v_mfma_f32_16x16x32_bf16 v[100:103], v[180:183], v[228:231], v[100:103]
	v_mfma_f32_16x16x32_bf16 v[92:95], v[136:139], v[236:239], v[92:95]
	v_mfma_f32_16x16x32_bf16 v[84:87], v[180:183], v[236:239], v[84:87]
	v_mfma_f32_16x16x32_bf16 v[76:79], v[136:139], v[244:247], v[76:79]
	v_mfma_f32_16x16x32_bf16 v[68:71], v[180:183], v[244:247], v[68:71]
	v_mfma_f32_16x16x32_bf16 v[120:123], v[200:203], v[216:219], v[120:123]
	v_mfma_f32_16x16x32_bf16 v[112:115], v[208:211], v[216:219], v[112:115]
	v_mfma_f32_16x16x32_bf16 v[104:107], v[200:203], v[224:227], v[104:107]
	v_mfma_f32_16x16x32_bf16 v[96:99], v[208:211], v[224:227], v[96:99]
	v_mfma_f32_16x16x32_bf16 v[88:91], v[200:203], v[232:235], v[88:91]
	v_mfma_f32_16x16x32_bf16 v[80:83], v[208:211], v[232:235], v[80:83]
	v_mfma_f32_16x16x32_bf16 v[72:75], v[200:203], v[240:243], v[72:75]
	v_mfma_f32_16x16x32_bf16 v[64:67], v[208:211], v[240:243], v[64:67]
	v_mfma_f32_16x16x32_bf16 v[120:123], v[204:207], v[220:223], v[120:123]
	v_mfma_f32_16x16x32_bf16 v[112:115], v[212:215], v[220:223], v[112:115]
	v_mfma_f32_16x16x32_bf16 v[104:107], v[204:207], v[228:231], v[104:107]
	v_mfma_f32_16x16x32_bf16 v[96:99], v[212:215], v[228:231], v[96:99]
	v_mfma_f32_16x16x32_bf16 v[88:91], v[204:207], v[236:239], v[88:91]
	v_mfma_f32_16x16x32_bf16 v[80:83], v[212:215], v[236:239], v[80:83]
	v_mfma_f32_16x16x32_bf16 v[72:75], v[204:207], v[244:247], v[72:75]
	v_mfma_f32_16x16x32_bf16 v[64:67], v[212:215], v[244:247], v[64:67]
	s_barrier
	s_add_i32 s6, s58, s26
	v_lshl_add_u64 v[168:169], v[168:169], 0, s[94:95]
	s_mov_b32 m0, s6
	ds_read_b128 v[216:219], v197 offset:49152
	ds_read_b128 v[220:223], v197 offset:50176
	ds_read_b128 v[224:227], v197 offset:51200
	ds_read_b128 v[228:231], v197 offset:52224
	ds_read_b128 v[232:235], v197 offset:53248
	ds_read_b128 v[236:239], v197 offset:54272
	ds_read_b128 v[240:243], v197 offset:55296
	ds_read_b128 v[244:247], v197 offset:56320
	global_load_lds_dwordx4 v[168:169], off
	s_add_i32 m0, s6, 0x2000
	s_add_u32 s0, s0, 0x40080
	v_lshl_add_u64 v[168:169], v[172:173], 0, s[94:95]
	s_addc_u32 s1, s1, 0
	s_add_i32 s6, s59, s26
	global_load_lds_dwordx4 v[168:169], off
	v_lshl_add_u64 v[168:169], s[0:1], 0, v[144:145]
	s_mov_b32 m0, s6
	s_nop 0
	global_load_lds_dwordx4 v[168:169], off
	v_lshl_add_u64 v[168:169], s[0:1], 0, v[150:151]
	s_add_i32 m0, s6, 0x2000
	s_nop 0
	global_load_lds_dwordx4 v[168:169], off
	v_lshl_add_u64 v[168:169], v[184:185], 0, s[94:95]
	s_mov_b32 m0, s31
	s_nop 0
	global_load_lds_dwordx4 v[168:169], off
	v_lshl_add_u64 v[168:169], v[186:187], 0, s[94:95]
	s_mov_b32 m0, s34
	s_nop 0
	global_load_lds_dwordx4 v[168:169], off
	s_waitcnt vmcnt(8)
	s_waitcnt lgkmcnt(0)
	.p2alignl 3, 3212836864
	s_barrier
	v_mfma_f32_16x16x32_bf16 v[60:63], v[132:135], v[216:219], v[60:63]
	v_mfma_f32_16x16x32_bf16 v[52:55], v[140:143], v[216:219], v[52:55]
	v_mfma_f32_16x16x32_bf16 v[44:47], v[132:135], v[224:227], v[44:47]
	v_mfma_f32_16x16x32_bf16 v[36:39], v[140:143], v[224:227], v[36:39]
	v_mfma_f32_16x16x32_bf16 v[28:31], v[132:135], v[232:235], v[28:31]
	v_mfma_f32_16x16x32_bf16 v[20:23], v[140:143], v[232:235], v[20:23]
	v_mfma_f32_16x16x32_bf16 v[12:15], v[132:135], v[240:243], v[12:15]
	v_mfma_f32_16x16x32_bf16 v[4:7], v[140:143], v[240:243], v[4:7]
	v_mfma_f32_16x16x32_bf16 v[60:63], v[136:139], v[220:223], v[60:63]
	v_mfma_f32_16x16x32_bf16 v[52:55], v[180:183], v[220:223], v[52:55]
	v_mfma_f32_16x16x32_bf16 v[44:47], v[136:139], v[228:231], v[44:47]
	v_mfma_f32_16x16x32_bf16 v[36:39], v[180:183], v[228:231], v[36:39]
	v_mfma_f32_16x16x32_bf16 v[28:31], v[136:139], v[236:239], v[28:31]
	v_mfma_f32_16x16x32_bf16 v[20:23], v[180:183], v[236:239], v[20:23]
	v_mfma_f32_16x16x32_bf16 v[12:15], v[136:139], v[244:247], v[12:15]
	v_mfma_f32_16x16x32_bf16 v[4:7], v[180:183], v[244:247], v[4:7]
	v_mfma_f32_16x16x32_bf16 v[56:59], v[200:203], v[216:219], v[56:59]
	v_mfma_f32_16x16x32_bf16 v[48:51], v[208:211], v[216:219], v[48:51]
	v_mfma_f32_16x16x32_bf16 v[40:43], v[200:203], v[224:227], v[40:43]
	v_mfma_f32_16x16x32_bf16 v[32:35], v[208:211], v[224:227], v[32:35]
	v_mfma_f32_16x16x32_bf16 v[24:27], v[200:203], v[232:235], v[24:27]
	v_mfma_f32_16x16x32_bf16 v[16:19], v[208:211], v[232:235], v[16:19]
	v_mfma_f32_16x16x32_bf16 v[8:11], v[200:203], v[240:243], v[8:11]
	v_mfma_f32_16x16x32_bf16 v[0:3], v[208:211], v[240:243], v[0:3]
	v_mfma_f32_16x16x32_bf16 v[56:59], v[204:207], v[220:223], v[56:59]
	v_mfma_f32_16x16x32_bf16 v[48:51], v[212:215], v[220:223], v[48:51]
	v_mfma_f32_16x16x32_bf16 v[40:43], v[204:207], v[228:231], v[40:43]
	v_mfma_f32_16x16x32_bf16 v[32:35], v[212:215], v[228:231], v[32:35]
	v_mfma_f32_16x16x32_bf16 v[24:27], v[204:207], v[236:239], v[24:27]
	v_mfma_f32_16x16x32_bf16 v[16:19], v[212:215], v[236:239], v[16:19]
	v_mfma_f32_16x16x32_bf16 v[8:11], v[204:207], v[244:247], v[8:11]
	v_mfma_f32_16x16x32_bf16 v[0:3], v[212:215], v[244:247], v[0:3]
	s_barrier
	s_add_i32 s57, s57, 2
	s_add_u32 s4, s4, 0x100
	s_addc_u32 s5, s5, 0
	s_add_u32 s55, s55, 0x100
	s_addc_u32 s56, s56, 0
	s_cmp_gt_u32 s57, 13
	s_cbranch_scc1 .LBB0_1650

; #define PG8_STAGE(bufoff, gbase, voff) do { _Pragma("unroll") for (int _i = 0; _i < 2; ++_i) \
;         __builtin_amdgcn_global_load_lds((const unsigned*)((const char*)(gbase) + (voff)[_i]), (PG8_LAS unsigned*)(lds + (bufoff) + ldsw + _i * 8192), 16, 0, 0); } while (0)
; #define PG8_LDA(dst, b, h) do { _Pragma("unroll") for (int m = 0; m < 4; ++m) _Pragma("unroll") for (int k = 0; k < 2; ++k) dst[m][k] = *(const PG8_LAS bf16x8*)(lds + PG8_SA(b, h) + aoff + m * 2048 + k * 1024); } while (0)
; #define PG8_LDB(dst, b, h) do { _Pragma("unroll") for (int n = 0; n < 2; ++n) _Pragma("unroll") for (int k = 0; k < 2; ++k) dst[n][k] = *(const PG8_LAS bf16x8*)(lds + PG8_SB(b, h) + boff + n * 2048 + k * 1024); } while (0)
; #define PG8_MMA(ai, bj, At, Bt) do { __builtin_amdgcn_s_setprio(1); _Pragma("unroll") for (int m = 0; m < 4; ++m) _Pragma("unroll") for (int n = 0; n < 2; ++n) _Pragma("unroll") for (int k = 0; k < 2; ++k) \
;         acc[ai][bj][m][n] = __builtin_amdgcn_mfma_f32_16x16x32_bf16(Bt[n][k], At[m][k], acc[ai][bj][m][n], 0, 0, 0); __builtin_amdgcn_s_setprio(0); } while (0)
; #define PG8_WAIT_V(n) asm volatile("s_waitcnt vmcnt(" #n ")" ::: "memory")
; #define PG8_BAR __builtin_amdgcn_s_barrier()
; template <class Epi, class Sched, bool ALIGN_EPI = false, bool SP2 = false>
; __device__ __forceinline__ void gemm_phase(PG8_LAS unsigned char* lds, const Gemm g, const Sched& S, const Epi& E) {
;     ...
;             const bool last = (t == nt - 2);
;             const char* a1 = cA + (size_t)(t + 1) * kstep;
;             const char* a2 = last ? nA : cA + (size_t)(t + 2) * kstep; const char* b2 = last ? nB : cB + (size_t)(t + 2) * kstep;
;             const char* a3 = a2 + kstep; const char* b3 = b2 + kstep;
;             if (last && has_next) S.a_ready(nxt);
;             if (last) E.pre(cur, wid, lane);
;             if constexpr (SP2) {
;             PG8_LDB(B0, 0, 0); PG8_LDB(B1, 0, 1); PG8_SCHED; PG8_LDA(At, 0, 0); PG8_STAGE(PG8_SA(1, 1), a1 + hstep, voffA);
;             PG8_WAIT_V(8); PG8_WAIT_L(0); PG8_BAR; PG8_MMA(0, 0, At, B0); PG8_MMA(0, 1, At, B1); PG8_BAR; PG8_SCHED;
;             PG8_LDA(At, 0, 1); PG8_STAGE(PG8_SB(0, 0), b2, voffB); PG8_STAGE(PG8_SB(0, 1), b2 + hstep, voffB); PG8_STAGE(PG8_SA(0, 0), a2, voffA);
;             PG8_WAIT_V(8); PG8_WAIT_L(0); PG8_BAR; PG8_MMA(1, 0, At, B0); PG8_MMA(1, 1, At, B1); PG8_BAR; PG8_SCHED;
.LBB0_1900:
	s_add_u32 s0, s6, 0x100
	s_addc_u32 s1, s7, 0
	s_add_i32 s60, 0, 0x10000
	s_cmp_eq_u32 s59, 40
	s_cselect_b32 s25, s41, s1
	s_cselect_b32 s24, s40, s0
	s_cselect_b32 s5, s49, s58
	s_cselect_b32 s4, s48, s57
	s_add_i32 s61, 0, 0x14000
	v_add_u32_e32 v160, s60, v143
	v_add_u32_e32 v172, s61, v143
	ds_read_b128 v[138:141], v160
	ds_read_b128 v[152:155], v160 offset:1024
	ds_read_b128 v[156:159], v160 offset:2048
	ds_read_b128 v[160:163], v160 offset:3072
	ds_read_b128 v[164:167], v172
	ds_read_b128 v[168:171], v172 offset:1024
	ds_read_b128 v[180:183], v172 offset:2048
	ds_read_b128 v[198:201], v172 offset:3072
	v_lshl_add_u64 v[172:173], s[6:7], 0, v[134:135]
	s_add_i32 m0, s30, 0xc000
	ds_read_b128 v[202:205], v151
	ds_read_b128 v[206:209], v151 offset:1024
	ds_read_b128 v[210:213], v151 offset:2048
	ds_read_b128 v[214:217], v151 offset:3072
	ds_read_b128 v[218:221], v151 offset:4096
	ds_read_b128 v[222:225], v151 offset:5120
	ds_read_b128 v[226:229], v151 offset:6144
	ds_read_b128 v[230:233], v151 offset:7168
	global_load_lds_dwordx4 v[172:173], off
	v_lshl_add_u64 v[172:173], s[6:7], 0, v[136:137]
	s_add_i32 m0, s30, 0xe000
	s_nop 0
	global_load_lds_dwordx4 v[172:173], off
	s_waitcnt vmcnt(8)
	s_waitcnt lgkmcnt(0)
	.p2alignl 3, 3212836864
	s_barrier
	v_mfma_f32_16x16x32_bf16 v[124:127], v[138:141], v[202:205], v[124:127]
	v_mfma_f32_16x16x32_bf16 v[120:123], v[156:159], v[202:205], v[120:123]
	v_mfma_f32_16x16x32_bf16 v[108:111], v[138:141], v[210:213], v[108:111]
	v_mfma_f32_16x16x32_bf16 v[104:107], v[156:159], v[210:213], v[104:107]
	v_mfma_f32_16x16x32_bf16 v[92:95], v[138:141], v[218:221], v[92:95]
	v_mfma_f32_16x16x32_bf16 v[88:91], v[156:159], v[218:221], v[88:91]
	v_mfma_f32_16x16x32_bf16 v[76:79], v[138:141], v[226:229], v[76:79]
	v_mfma_f32_16x16x32_bf16 v[72:75], v[156:159], v[226:229], v[72:75]
	v_mfma_f32_16x16x32_bf16 v[124:127], v[152:155], v[206:209], v[124:127]
	v_mfma_f32_16x16x32_bf16 v[120:123], v[160:163], v[206:209], v[120:123]
	v_mfma_f32_16x16x32_bf16 v[108:111], v[152:155], v[214:217], v[108:111]
	v_mfma_f32_16x16x32_bf16 v[104:107], v[160:163], v[214:217], v[104:107]
	v_mfma_f32_16x16x32_bf16 v[92:95], v[152:155], v[222:225], v[92:95]
	v_mfma_f32_16x16x32_bf16 v[88:91], v[160:163], v[222:225], v[88:91]
	v_mfma_f32_16x16x32_bf16 v[76:79], v[152:155], v[230:233], v[76:79]
	v_mfma_f32_16x16x32_bf16 v[72:75], v[160:163], v[230:233], v[72:75]
	v_mfma_f32_16x16x32_bf16 v[116:119], v[164:167], v[202:205], v[116:119]
	v_mfma_f32_16x16x32_bf16 v[112:115], v[180:183], v[202:205], v[112:115]
	v_mfma_f32_16x16x32_bf16 v[100:103], v[164:167], v[210:213], v[100:103]
	v_mfma_f32_16x16x32_bf16 v[96:99], v[180:183], v[210:213], v[96:99]
	v_mfma_f32_16x16x32_bf16 v[84:87], v[164:167], v[218:221], v[84:87]
	v_mfma_f32_16x16x32_bf16 v[80:83], v[180:183], v[218:221], v[80:83]
	v_mfma_f32_16x16x32_bf16 v[68:71], v[164:167], v[226:229], v[68:71]
	v_mfma_f32_16x16x32_bf16 v[64:67], v[180:183], v[226:229], v[64:67]
	v_mfma_f32_16x16x32_bf16 v[116:119], v[168:171], v[206:209], v[116:119]
	v_mfma_f32_16x16x32_bf16 v[112:115], v[198:201], v[206:209], v[112:115]
	v_mfma_f32_16x16x32_bf16 v[100:103], v[168:171], v[214:217], v[100:103]
	v_mfma_f32_16x16x32_bf16 v[96:99], v[198:201], v[214:217], v[96:99]
	v_mfma_f32_16x16x32_bf16 v[84:87], v[168:171], v[222:225], v[84:87]
	v_mfma_f32_16x16x32_bf16 v[80:83], v[198:201], v[222:225], v[80:83]
	v_mfma_f32_16x16x32_bf16 v[68:71], v[168:171], v[230:233], v[68:71]
	v_mfma_f32_16x16x32_bf16 v[64:67], v[198:201], v[230:233], v[64:67]
	s_barrier
	s_add_i32 s6, s60, s29
	v_lshl_add_u64 v[172:173], s[4:5], 0, v[144:145]
	s_mov_b32 m0, s6
	ds_read_b128 v[202:205], v151 offset:16384
	ds_read_b128 v[206:209], v151 offset:17408
	ds_read_b128 v[210:213], v151 offset:18432
	ds_read_b128 v[214:217], v151 offset:19456
	ds_read_b128 v[218:221], v151 offset:20480
	ds_read_b128 v[222:225], v151 offset:21504
	ds_read_b128 v[226:229], v151 offset:22528
	ds_read_b128 v[230:233], v151 offset:23552
	global_load_lds_dwordx4 v[172:173], off
	s_add_i32 m0, s6, 0x2000
	s_add_u32 s6, s4, 0xb0000
	v_lshl_add_u64 v[184:185], s[4:5], 0, v[128:129]
	s_addc_u32 s7, s5, 0
	s_add_i32 s60, s61, s29
	global_load_lds_dwordx4 v[184:185], off
	v_lshl_add_u64 v[186:187], s[6:7], 0, v[144:145]
	s_mov_b32 m0, s60
	v_lshl_add_u64 v[188:189], s[24:25], 0, v[130:131]
	global_load_lds_dwordx4 v[186:187], off
	v_lshl_add_u64 v[186:187], s[6:7], 0, v[128:129]
	s_add_i32 m0, s60, 0x2000
	s_nop 0
	global_load_lds_dwordx4 v[186:187], off
	v_lshl_add_u64 v[186:187], s[24:25], 0, v[132:133]
	s_mov_b32 m0, s30
	s_nop 0
	global_load_lds_dwordx4 v[186:187], off
	s_mov_b32 m0, s31
	s_nop 0
	global_load_lds_dwordx4 v[188:189], off
	s_waitcnt vmcnt(8)
	s_waitcnt lgkmcnt(0)
	.p2alignl 3, 3212836864
	s_barrier
; #define PG8_STAGE(bufoff, gbase, voff) do { _Pragma("unroll") for (int _i = 0; _i < 2; ++_i) \
;         __builtin_amdgcn_global_load_lds((const unsigned*)((const char*)(gbase) + (voff)[_i]), (PG8_LAS unsigned*)(lds + (bufoff) + ldsw + _i * 8192), 16, 0, 0); } while (0)
; #define PG8_LDA(dst, b, h) do { _Pragma("unroll") for (int m = 0; m < 4; ++m) _Pragma("unroll") for (int k = 0; k < 2; ++k) dst[m][k] = *(const PG8_LAS bf16x8*)(lds + PG8_SA(b, h) + aoff + m * 2048 + k * 1024); } while (0)
; #define PG8_LDB(dst, b, h) do { _Pragma("unroll") for (int n = 0; n < 2; ++n) _Pragma("unroll") for (int k = 0; k < 2; ++k) dst[n][k] = *(const PG8_LAS bf16x8*)(lds + PG8_SB(b, h) + boff + n * 2048 + k * 1024); } while (0)
; #define PG8_MMA(ai, bj, At, Bt) do { __builtin_amdgcn_s_setprio(1); _Pragma("unroll") for (int m = 0; m < 4; ++m) _Pragma("unroll") for (int n = 0; n < 2; ++n) _Pragma("unroll") for (int k = 0; k < 2; ++k) \
;         acc[ai][bj][m][n] = __builtin_amdgcn_mfma_f32_16x16x32_bf16(Bt[n][k], At[m][k], acc[ai][bj][m][n], 0, 0, 0); __builtin_amdgcn_s_setprio(0); } while (0)
; #define PG8_WAIT_V(n) asm volatile("s_waitcnt vmcnt(" #n ")" ::: "memory")
; #define PG8_WAIT_L(n) asm volatile("s_waitcnt lgkmcnt(" #n ")" ::: "memory")
; #define PG8_BAR __builtin_amdgcn_s_barrier()
; #define PG8_SCHED __builtin_amdgcn_sched_barrier(0)
; template <class Epi, class Sched, bool ALIGN_EPI = false, bool SP2 = false>
; __device__ __forceinline__ void gemm_phase(PG8_LAS unsigned char* lds, const Gemm g, const Sched& S, const Epi& E) {
;     ...
;             PG8_WAIT_V(8); PG8_WAIT_L(0); PG8_BAR; PG8_MMA(1, 0, At, B0); PG8_MMA(1, 1, At, B1); PG8_BAR; PG8_SCHED;
;             PG8_LDB(B0, 1, 0); PG8_LDB(B1, 1, 1); PG8_SCHED; PG8_LDA(At, 1, 0); PG8_STAGE(PG8_SA(0, 1), a2 + hstep, voffA);
;             PG8_WAIT_V(8); PG8_WAIT_L(0); PG8_BAR; PG8_MMA(0, 0, At, B0); PG8_MMA(0, 1, At, B1); PG8_BAR; PG8_SCHED;
	v_mfma_f32_16x16x32_bf16 v[60:63], v[138:141], v[202:205], v[60:63]
	v_mfma_f32_16x16x32_bf16 v[56:59], v[156:159], v[202:205], v[56:59]
	v_mfma_f32_16x16x32_bf16 v[44:47], v[138:141], v[210:213], v[44:47]
	v_mfma_f32_16x16x32_bf16 v[40:43], v[156:159], v[210:213], v[40:43]
	v_mfma_f32_16x16x32_bf16 v[28:31], v[138:141], v[218:221], v[28:31]
	v_mfma_f32_16x16x32_bf16 v[24:27], v[156:159], v[218:221], v[24:27]
	v_mfma_f32_16x16x32_bf16 v[12:15], v[138:141], v[226:229], v[12:15]
	v_mfma_f32_16x16x32_bf16 v[8:11], v[156:159], v[226:229], v[8:11]
	v_mfma_f32_16x16x32_bf16 v[60:63], v[152:155], v[206:209], v[60:63]
	v_mfma_f32_16x16x32_bf16 v[56:59], v[160:163], v[206:209], v[56:59]
	v_mfma_f32_16x16x32_bf16 v[44:47], v[152:155], v[214:217], v[44:47]
	v_mfma_f32_16x16x32_bf16 v[40:43], v[160:163], v[214:217], v[40:43]
	v_mfma_f32_16x16x32_bf16 v[28:31], v[152:155], v[222:225], v[28:31]
	v_mfma_f32_16x16x32_bf16 v[24:27], v[160:163], v[222:225], v[24:27]
	v_mfma_f32_16x16x32_bf16 v[12:15], v[152:155], v[230:233], v[12:15]
	v_mfma_f32_16x16x32_bf16 v[8:11], v[160:163], v[230:233], v[8:11]
	v_mfma_f32_16x16x32_bf16 v[52:55], v[164:167], v[202:205], v[52:55]
	v_mfma_f32_16x16x32_bf16 v[48:51], v[180:183], v[202:205], v[48:51]
	v_mfma_f32_16x16x32_bf16 v[36:39], v[164:167], v[210:213], v[36:39]
	v_mfma_f32_16x16x32_bf16 v[32:35], v[180:183], v[210:213], v[32:35]
	v_mfma_f32_16x16x32_bf16 v[20:23], v[164:167], v[218:221], v[20:23]
	v_mfma_f32_16x16x32_bf16 v[16:19], v[180:183], v[218:221], v[16:19]
	v_mfma_f32_16x16x32_bf16 v[4:7], v[164:167], v[226:229], v[4:7]
	v_mfma_f32_16x16x32_bf16 v[0:3], v[180:183], v[226:229], v[0:3]
	v_mfma_f32_16x16x32_bf16 v[52:55], v[168:171], v[206:209], v[52:55]
	v_mfma_f32_16x16x32_bf16 v[48:51], v[198:201], v[206:209], v[48:51]
	v_mfma_f32_16x16x32_bf16 v[36:39], v[168:171], v[214:217], v[36:39]
	v_mfma_f32_16x16x32_bf16 v[32:35], v[198:201], v[214:217], v[32:35]
	v_mfma_f32_16x16x32_bf16 v[20:23], v[168:171], v[222:225], v[20:23]
	v_mfma_f32_16x16x32_bf16 v[16:19], v[198:201], v[222:225], v[16:19]
	v_mfma_f32_16x16x32_bf16 v[4:7], v[168:171], v[230:233], v[4:7]
	v_mfma_f32_16x16x32_bf16 v[0:3], v[198:201], v[230:233], v[0:3]
	s_barrier
	s_add_i32 s60, 0, 0x18000
	s_add_i32 s61, 0, 0x1c000
	v_add_u32_e32 v160, s60, v143
	v_add_u32_e32 v190, s61, v143
	ds_read_b128 v[138:141], v160
	ds_read_b128 v[152:155], v160 offset:1024
	ds_read_b128 v[156:159], v160 offset:2048
	ds_read_b128 v[160:163], v160 offset:3072
	ds_read_b128 v[164:167], v190
	ds_read_b128 v[168:171], v190 offset:1024
	ds_read_b128 v[180:183], v190 offset:2048
	ds_read_b128 v[198:201], v190 offset:3072
	s_add_u32 s6, s24, 0xb0000
	s_addc_u32 s7, s25, 0
	s_mov_b32 m0, s34
	v_lshl_add_u64 v[190:191], s[6:7], 0, v[132:133]
	ds_read_b128 v[202:205], v151 offset:32768
	ds_read_b128 v[206:209], v151 offset:33792
	ds_read_b128 v[210:213], v151 offset:34816
	ds_read_b128 v[214:217], v151 offset:35840
	ds_read_b128 v[218:221], v151 offset:36864
	ds_read_b128 v[222:225], v151 offset:37888
	ds_read_b128 v[226:229], v151 offset:38912
	ds_read_b128 v[230:233], v151 offset:39936
	global_load_lds_dwordx4 v[190:191], off
	v_lshl_add_u64 v[190:191], s[6:7], 0, v[130:131]
	s_mov_b32 m0, s35
	s_nop 0
	global_load_lds_dwordx4 v[190:191], off
	s_waitcnt vmcnt(8)
	s_waitcnt lgkmcnt(0)
	.p2alignl 3, 3212836864
	s_barrier
	v_mfma_f32_16x16x32_bf16 v[124:127], v[138:141], v[202:205], v[124:127]
	v_mfma_f32_16x16x32_bf16 v[120:123], v[156:159], v[202:205], v[120:123]
	v_mfma_f32_16x16x32_bf16 v[108:111], v[138:141], v[210:213], v[108:111]
	v_mfma_f32_16x16x32_bf16 v[104:107], v[156:159], v[210:213], v[104:107]
	v_mfma_f32_16x16x32_bf16 v[92:95], v[138:141], v[218:221], v[92:95]
	v_mfma_f32_16x16x32_bf16 v[88:91], v[156:159], v[218:221], v[88:91]
	v_mfma_f32_16x16x32_bf16 v[76:79], v[138:141], v[226:229], v[76:79]
	v_mfma_f32_16x16x32_bf16 v[72:75], v[156:159], v[226:229], v[72:75]
	v_mfma_f32_16x16x32_bf16 v[124:127], v[152:155], v[206:209], v[124:127]
	v_mfma_f32_16x16x32_bf16 v[120:123], v[160:163], v[206:209], v[120:123]
	v_mfma_f32_16x16x32_bf16 v[108:111], v[152:155], v[214:217], v[108:111]
	v_mfma_f32_16x16x32_bf16 v[104:107], v[160:163], v[214:217], v[104:107]
	v_mfma_f32_16x16x32_bf16 v[92:95], v[152:155], v[222:225], v[92:95]
	v_mfma_f32_16x16x32_bf16 v[88:91], v[160:163], v[222:225], v[88:91]
	v_mfma_f32_16x16x32_bf16 v[76:79], v[152:155], v[230:233], v[76:79]
	v_mfma_f32_16x16x32_bf16 v[72:75], v[160:163], v[230:233], v[72:75]
	v_mfma_f32_16x16x32_bf16 v[116:119], v[164:167], v[202:205], v[116:119]
	v_mfma_f32_16x16x32_bf16 v[112:115], v[180:183], v[202:205], v[112:115]
	v_mfma_f32_16x16x32_bf16 v[100:103], v[164:167], v[210:213], v[100:103]
	v_mfma_f32_16x16x32_bf16 v[96:99], v[180:183], v[210:213], v[96:99]
	v_mfma_f32_16x16x32_bf16 v[84:87], v[164:167], v[218:221], v[84:87]
	v_mfma_f32_16x16x32_bf16 v[80:83], v[180:183], v[218:221], v[80:83]
	v_mfma_f32_16x16x32_bf16 v[68:71], v[164:167], v[226:229], v[68:71]
	v_mfma_f32_16x16x32_bf16 v[64:67], v[180:183], v[226:229], v[64:67]
	v_mfma_f32_16x16x32_bf16 v[116:119], v[168:171], v[206:209], v[116:119]
	v_mfma_f32_16x16x32_bf16 v[112:115], v[198:201], v[206:209], v[112:115]
	v_mfma_f32_16x16x32_bf16 v[100:103], v[168:171], v[214:217], v[100:103]
	v_mfma_f32_16x16x32_bf16 v[96:99], v[198:201], v[214:217], v[96:99]
	v_mfma_f32_16x16x32_bf16 v[84:87], v[168:171], v[222:225], v[84:87]
	v_mfma_f32_16x16x32_bf16 v[80:83], v[198:201], v[222:225], v[80:83]
	v_mfma_f32_16x16x32_bf16 v[68:71], v[168:171], v[230:233], v[68:71]
	v_mfma_f32_16x16x32_bf16 v[64:67], v[198:201], v[230:233], v[64:67]
	s_barrier
; #define PG8_STAGE(bufoff, gbase, voff) do { _Pragma("unroll") for (int _i = 0; _i < 2; ++_i) \
;         __builtin_amdgcn_global_load_lds((const unsigned*)((const char*)(gbase) + (voff)[_i]), (PG8_LAS unsigned*)(lds + (bufoff) + ldsw + _i * 8192), 16, 0, 0); } while (0)
; #define PG8_LDA(dst, b, h) do { _Pragma("unroll") for (int m = 0; m < 4; ++m) _Pragma("unroll") for (int k = 0; k < 2; ++k) dst[m][k] = *(const PG8_LAS bf16x8*)(lds + PG8_SA(b, h) + aoff + m * 2048 + k * 1024); } while (0)
; #define PG8_MMA(ai, bj, At, Bt) do { __builtin_amdgcn_s_setprio(1); _Pragma("unroll") for (int m = 0; m < 4; ++m) _Pragma("unroll") for (int n = 0; n < 2; ++n) _Pragma("unroll") for (int k = 0; k < 2; ++k) \
;         acc[ai][bj][m][n] = __builtin_amdgcn_mfma_f32_16x16x32_bf16(Bt[n][k], At[m][k], acc[ai][bj][m][n], 0, 0, 0); __builtin_amdgcn_s_setprio(0); } while (0)
; #define PG8_WAIT_V(n) asm volatile("s_waitcnt vmcnt(" #n ")" ::: "memory")
; #define PG8_WAIT_L(n) asm volatile("s_waitcnt lgkmcnt(" #n ")" ::: "memory")
; #define PG8_BAR __builtin_amdgcn_s_barrier()
; #define PG8_SCHED __builtin_amdgcn_sched_barrier(0)
; template <class Epi, class Sched, bool ALIGN_EPI = false, bool SP2 = false>
; __device__ __forceinline__ void gemm_phase(PG8_LAS unsigned char* lds, const Gemm g, const Sched& S, const Epi& E) {
;     ...
;         for (int t = 0; t < nt; t += 2) {
;             const bool last = (t == nt - 2);
;     ...
;             PG8_LDA(At, 1, 1); PG8_STAGE(PG8_SB(1, 0), b3, voffB); PG8_STAGE(PG8_SB(1, 1), b3 + hstep, voffB); PG8_STAGE(PG8_SA(1, 0), a3, voffA);
;             PG8_WAIT_V(8); PG8_WAIT_L(0); PG8_BAR; PG8_MMA(1, 0, At, B0); PG8_MMA(1, 1, At, B1); PG8_BAR; PG8_SCHED;
	s_add_i32 s6, s60, s29
	v_lshl_add_u64 v[172:173], v[172:173], 0, s[94:95]
	s_mov_b32 m0, s6
	ds_read_b128 v[202:205], v151 offset:49152
	ds_read_b128 v[206:209], v151 offset:50176
	ds_read_b128 v[210:213], v151 offset:51200
	ds_read_b128 v[214:217], v151 offset:52224
	ds_read_b128 v[218:221], v151 offset:53248
	ds_read_b128 v[222:225], v151 offset:54272
	ds_read_b128 v[226:229], v151 offset:55296
	ds_read_b128 v[230:233], v151 offset:56320
	global_load_lds_dwordx4 v[172:173], off
	s_add_i32 m0, s6, 0x2000
	s_add_u32 s4, s4, 0xb0080
	v_lshl_add_u64 v[172:173], v[184:185], 0, s[94:95]
	s_addc_u32 s5, s5, 0
	s_add_i32 s6, s61, s29
	global_load_lds_dwordx4 v[172:173], off
	v_lshl_add_u64 v[172:173], s[4:5], 0, v[144:145]
	s_mov_b32 m0, s6
	s_nop 0
	global_load_lds_dwordx4 v[172:173], off
	v_lshl_add_u64 v[172:173], s[4:5], 0, v[128:129]
	s_add_i32 m0, s6, 0x2000
	s_nop 0
	global_load_lds_dwordx4 v[172:173], off
	v_lshl_add_u64 v[172:173], v[186:187], 0, s[94:95]
	s_mov_b32 m0, s50
	s_nop 0
	global_load_lds_dwordx4 v[172:173], off
	v_lshl_add_u64 v[172:173], v[188:189], 0, s[94:95]
	s_mov_b32 m0, s51
	s_nop 0
	global_load_lds_dwordx4 v[172:173], off
	s_waitcnt vmcnt(8)
	s_waitcnt lgkmcnt(0)
	.p2alignl 3, 3212836864
	s_barrier
	v_mfma_f32_16x16x32_bf16 v[60:63], v[138:141], v[202:205], v[60:63]
	v_mfma_f32_16x16x32_bf16 v[56:59], v[156:159], v[202:205], v[56:59]
	v_mfma_f32_16x16x32_bf16 v[44:47], v[138:141], v[210:213], v[44:47]
	v_mfma_f32_16x16x32_bf16 v[40:43], v[156:159], v[210:213], v[40:43]
	v_mfma_f32_16x16x32_bf16 v[28:31], v[138:141], v[218:221], v[28:31]
	v_mfma_f32_16x16x32_bf16 v[24:27], v[156:159], v[218:221], v[24:27]
	v_mfma_f32_16x16x32_bf16 v[12:15], v[138:141], v[226:229], v[12:15]
	v_mfma_f32_16x16x32_bf16 v[8:11], v[156:159], v[226:229], v[8:11]
	v_mfma_f32_16x16x32_bf16 v[60:63], v[152:155], v[206:209], v[60:63]
	v_mfma_f32_16x16x32_bf16 v[56:59], v[160:163], v[206:209], v[56:59]
	v_mfma_f32_16x16x32_bf16 v[44:47], v[152:155], v[214:217], v[44:47]
	v_mfma_f32_16x16x32_bf16 v[40:43], v[160:163], v[214:217], v[40:43]
	v_mfma_f32_16x16x32_bf16 v[28:31], v[152:155], v[222:225], v[28:31]
	v_mfma_f32_16x16x32_bf16 v[24:27], v[160:163], v[222:225], v[24:27]
	v_mfma_f32_16x16x32_bf16 v[12:15], v[152:155], v[230:233], v[12:15]
	v_mfma_f32_16x16x32_bf16 v[8:11], v[160:163], v[230:233], v[8:11]
	v_mfma_f32_16x16x32_bf16 v[52:55], v[164:167], v[202:205], v[52:55]
	v_mfma_f32_16x16x32_bf16 v[48:51], v[180:183], v[202:205], v[48:51]
	v_mfma_f32_16x16x32_bf16 v[36:39], v[164:167], v[210:213], v[36:39]
	v_mfma_f32_16x16x32_bf16 v[32:35], v[180:183], v[210:213], v[32:35]
	v_mfma_f32_16x16x32_bf16 v[20:23], v[164:167], v[218:221], v[20:23]
	v_mfma_f32_16x16x32_bf16 v[16:19], v[180:183], v[218:221], v[16:19]
	v_mfma_f32_16x16x32_bf16 v[4:7], v[164:167], v[226:229], v[4:7]
	v_mfma_f32_16x16x32_bf16 v[0:3], v[180:183], v[226:229], v[0:3]
	v_mfma_f32_16x16x32_bf16 v[52:55], v[168:171], v[206:209], v[52:55]
	v_mfma_f32_16x16x32_bf16 v[48:51], v[198:201], v[206:209], v[48:51]
	v_mfma_f32_16x16x32_bf16 v[36:39], v[168:171], v[214:217], v[36:39]
	v_mfma_f32_16x16x32_bf16 v[32:35], v[198:201], v[214:217], v[32:35]
	v_mfma_f32_16x16x32_bf16 v[20:23], v[168:171], v[222:225], v[20:23]
	v_mfma_f32_16x16x32_bf16 v[16:19], v[198:201], v[222:225], v[16:19]
	v_mfma_f32_16x16x32_bf16 v[4:7], v[168:171], v[230:233], v[4:7]
	v_mfma_f32_16x16x32_bf16 v[0:3], v[198:201], v[230:233], v[0:3]
	s_barrier
	s_add_i32 s59, s59, 2
	s_add_u32 s57, s57, 0x100
	s_addc_u32 s58, s58, 0
	s_cmp_gt_u32 s59, 41
	s_mov_b64 s[6:7], s[0:1]
	s_cbranch_scc0 .LBB0_1900
	s_and_b64 vcc, exec, s[46:47]
	s_cbranch_vccz .LBB0_1903
	s_barrier
